# SWA item: gate/sink prefetch issued after the K/V staging wait so the staging burst is 1/3 smaller (no setprio)
# baseline (speedup 1.0000x reference)
; #define LAS __attribute__((address_space(3)))
; template <bool FIRST>
; __device__ __forceinline__ void swa_item(const Params& p, int l, LAS unsigned char* lds, int item, int tid, int wave, int lane) {
;     ...
;     const int tok = tb + wave * 16 + r;
;     h8 qfa[4][2];
; #pragma unroll
;     for (int gi = 0; gi < 4; ++gi)
; #pragma unroll
;         for (int ks = 0; ks < 2; ++ks) qfa[gi][ks] = *(const h8*)(PR + (size_t)tok * NIN + C_SQ + (kvh * 4 + gi) * 64 + ks * 32 + g * 8);
; #pragma unroll
;     for (int i = 0; i < 4; ++i) { const int id = tid + 512 * i, row = id >> 3, ch = id & 7;
;         h8 kk = z8, vv = z8;
;         if (nb > 0 || row >= 128) { const half_t* src = PR + (size_t)(tb - 128 + row) * NIN + kvh * 64 + ch * 8; kk = *(const h8*)(src + C_SK); vv = *(const h8*)(src + C_SV); }
;         *(LAS h8*)(Ks + row * SSTR + ch * 8) = kk; *(LAS h8*)(Vs + row * SSTR + ch * 8) = vv; }
;     if (tid < 128) { const int row = 256 + (tid >> 3), ch = tid & 7; *(LAS h8*)(Ks + row * SSTR + ch * 8) = z8; *(LAS h8*)(Vs + row * SSTR + ch * 8) = z8; }
;     __syncthreads();
;     ...
;         for (int mt = 0; mt < 4; ++mt) { const int col = hq * 64 + mt * 16 + 4 * g;
;             const h4 sg = *(const h4*)(PR + (size_t)tok * NIN + C_SG + col);
.LBB0_393:
	s_and_b64 vcc, exec, s[0:1]
	s_cbranch_vccz .LBB0_388
	s_and_b32 s0, s9, 0xf8
	s_cmp_lg_u32 s0, 0
	v_lshlrev_b32_e32 v2, 1, v74
	s_cbranch_scc0 .LBB0_406
	s_bfe_u32 s4, s9, 0x50003
	s_lshl_b32 s0, s9, 4
	s_and_b32 s0, s0, 0xfffff000
	s_lshl_b32 s1, s4, 7
	s_or_b32 s11, s1, s0
	v_add_u32_e32 v0, s11, v100
	v_mov_b64_e32 v[4:5], s[36:37]
	s_and_b32 s10, s9, 7
	v_mad_i64_i32 v[38:39], s[0:1], v0, s35, v[4:5]
	v_lshl_add_u64 v[4:5], v[38:39], 0, v[2:3]
	s_lshl_b32 s20, s10, 9
	v_lshl_add_u64 v[4:5], v[4:5], 0, s[20:21]
	s_mov_b64 s[0:1], 0x3000
	v_lshl_add_u64 v[8:9], v[4:5], 0, s[0:1]
	s_movk_i32 s0, 0x3000
	v_add_co_u32_e32 v10, vcc, s0, v4
	s_cmp_lg_u32 s4, 0
	s_nop 0
	v_addc_co_u32_e32 v11, vcc, 0, v5, vcc
	global_load_dwordx4 v[56:59], v[8:9], off offset:64
	global_load_dwordx4 v[24:27], v[8:9], off offset:128
	global_load_dwordx4 v[20:23], v[8:9], off offset:192
	global_load_dwordx4 v[16:19], v[8:9], off offset:256
	global_load_dwordx4 v[12:15], v[8:9], off offset:320
	global_load_dwordx4 v[4:7], v[8:9], off offset:384
	global_load_dwordx4 v[60:63], v[10:11], off
	s_nop 0
	global_load_dwordx4 v[8:11], v[8:9], off offset:448
	s_lshl_b32 s20, s10, 7
	s_addk_i32 s11, 0xff80
	v_lshl_add_u64 v[40:41], v[76:77], 0, s[20:21]
	s_mov_b64 s[12:13], 0x4000
	v_lshl_add_u64 v[40:41], v[40:41], 0, s[12:13]
	v_add_u32_e32 v1, s11, v75
	v_mad_i64_i32 v[42:43], s[0:1], v1, s35, v[40:41]
	v_add_u32_e32 v1, s11, v71
	v_mad_i64_i32 v[44:45], s[0:1], v1, s35, v[40:41]
	v_add_u32_e32 v1, s11, v79
	v_mad_i64_i32 v[46:47], s[0:1], v1, s35, v[40:41]
	v_add_u32_e32 v1, s11, v81
	v_mad_i64_i32 v[224:225], s[0:1], v1, s35, v[40:41]
	global_load_dwordx4 v[128:131], v[42:43], off
	global_load_dwordx4 v[132:135], v[42:43], off offset:1024
	global_load_dwordx4 v[136:139], v[44:45], off
	global_load_dwordx4 v[140:143], v[44:45], off offset:1024
	global_load_dwordx4 v[144:147], v[46:47], off
	global_load_dwordx4 v[48:51], v[46:47], off offset:1024
	global_load_dwordx4 v[52:55], v[224:225], off
	global_load_dwordx4 v[64:67], v[224:225], off offset:1024
	s_lshl_b32 s4, s10, 8
	s_waitcnt vmcnt(0)
	ds_write_b128 v101, v[128:131]
	ds_write_b128 v101, v[132:135] offset:39168
	ds_write_b128 v78, v[136:139]
	ds_write_b128 v78, v[140:143] offset:39168
	ds_write_b128 v80, v[144:147]
	ds_write_b128 v80, v[48:51] offset:39168
	ds_write_b128 v82, v[52:55]
	ds_write_b128 v82, v[64:67] offset:39168
	s_lshl_b32 s12, s10, 2
	s_or_b32 s20, s12, s8
	s_lshl_b64 s[12:13], s[20:21], 2
	s_add_u32 s12, s94, s12
	s_addc_u32 s13, s95, s13
	global_load_dwordx4 v[170:173], v3, s[12:13]
	v_lshlrev_b32_e32 v174, 1, v99
	v_lshl_or_b32 v174, s10, 9, v174
	v_mov_b32_e32 v175, v3
	v_lshl_add_u64 v[174:175], v[38:39], 0, v[174:175]
	s_mov_b64 s[12:13], 0x4800
	v_lshl_add_u64 v[174:175], v[174:175], 0, s[12:13]
	global_load_dwordx2 v[192:193], v[174:175], off
	global_load_dwordx2 v[194:195], v[174:175], off offset:32
	global_load_dwordx2 v[196:197], v[174:175], off offset:64
	global_load_dwordx2 v[198:199], v[174:175], off offset:96
	global_load_dwordx2 v[200:201], v[174:175], off offset:128
	global_load_dwordx2 v[202:203], v[174:175], off offset:160
	global_load_dwordx2 v[204:205], v[174:175], off offset:192
	global_load_dwordx2 v[206:207], v[174:175], off offset:224
	global_load_dwordx2 v[208:209], v[174:175], off offset:256
	global_load_dwordx2 v[210:211], v[174:175], off offset:288
	global_load_dwordx2 v[212:213], v[174:175], off offset:320
	global_load_dwordx2 v[214:215], v[174:175], off offset:352
	global_load_dwordx2 v[216:217], v[174:175], off offset:384
	global_load_dwordx2 v[218:219], v[174:175], off offset:416
	global_load_dwordx2 v[220:221], v[174:175], off offset:448
	global_load_dwordx2 v[222:223], v[174:175], off offset:480
	s_and_saveexec_b64 s[0:1], s[46:47]
	s_cbranch_execz .LBB0_405
	s_mov_b32 s22, s21
	s_mov_b32 s23, s21
	s_mov_b32 s20, s21
	v_mov_b64_e32 v[30:31], s[22:23]
	v_mov_b64_e32 v[28:29], s[20:21]
	ds_write_b128 v83, v[28:31] offset:36864
	ds_write_b128 v102, v[28:31] offset:36864
.LBB0_405:
	s_or_b64 exec, exec, s[0:1]
	s_mov_b64 s[12:13], 0x4800
	v_ashrrev_i32_e32 v1, 31, v0
	v_lshl_add_u64 v[88:89], v[38:39], 0, s[12:13]
	v_readlane_b32 s12, v251, 17
	v_lshlrev_b64 v[0:1], 13, v[0:1]
	v_readlane_b32 s13, v251, 18
	v_readlane_b32 s14, v251, 19
	v_readlane_b32 s15, v251, 20
	s_lshl_b32 s0, s10, 2
	s_mov_b64 s[12:13], 0x26231000
	v_lshl_add_u64 v[0:1], s[14:15], 0, v[0:1]
	s_waitcnt lgkmcnt(0)
	s_barrier
; #define LAS __attribute__((address_space(3)))
; __device__ __forceinline__ float shx(float v, int lane, int m) { return __builtin_bit_cast(float, __builtin_amdgcn_ds_bpermute((lane ^ m) << 2, __builtin_bit_cast(int, v))); }
; __device__ __forceinline__ float ex2(float x) { return __builtin_amdgcn_exp2f(x); }
; template <bool FIRST>
; __device__ __forceinline__ void swa_item(const Params& p, int l, LAS unsigned char* lds, int item, int tid, int wave, int lane) {
;     ...
;         __builtin_amdgcn_sched_barrier(0);
;         h8 qf[2]; qf[0] = qfa[gi][0]; qf[1] = qfa[gi][1];
;         f32x4 s[9];
; #pragma unroll
;         for (int t = 0; t < 9; ++t) { s[t] = (f32x4){0.f, 0.f, 0.f, 0.f};
; #pragma unroll
;             for (int ks = 0; ks < 2; ++ks) { const h8 a = *(const LAS h8*)(Ks + ((wave + t) * 16 + r) * SSTR + ks * 32 + g * 8);
;                 s[t] = __builtin_amdgcn_mfma_f32_16x16x32_f16(a, qf[ks], s[t], 0, 0, 0); } }
;         const float SC2 = 0.125f * 1.44269504f;
;         const float sink2 = p.sinks[l * 32 + hq] * 1.44269504f;
;         const int rg4 = r - 4 * g;
; #pragma unroll
;         for (int e = 0; e < 4; ++e) { s[0][e] = (rg4 < e) ? s[0][e] : -INFINITY; s[8][e] = (rg4 >= e) ? s[8][e] : -INFINITY; }
;         if (FIRST) {
; #pragma unroll
;             for (int t = 0; t < 9; ++t) { const bool tile_ok = (wave + t >= 8);
; #pragma unroll
;                 for (int e = 0; e < 4; ++e) s[t][e] = tile_ok ? s[t][e] : -INFINITY; }
;         }
;         float mr = -INFINITY;
; #pragma unroll
;         for (int t = 0; t < 9; ++t)
; #pragma unroll
;             for (int e = 0; e < 4; ++e) mr = fmaxf(mr, s[t][e]);
;         mr = fmaxf(mr, shx(mr, lane, 16)); mr = fmaxf(mr, shx(mr, lane, 32));
;         const float m = fmaxf(mr * SC2, sink2);
;         float ls = 0.f;
; #pragma unroll
;         for (int t = 0; t < 9; ++t)
; #pragma unroll
;             for (int e = 0; e < 4; ++e) { const float pv = ex2(__builtin_fmaf(s[t][e], SC2, -m)); s[t][e] = pv; ls += pv; }
;         ls += shx(ls, lane, 16); ls += shx(ls, lane, 32);
;         ls += ex2(sink2 - m);
	v_lshl_add_u64 v[0:1], v[0:1], 0, s[12:13]
	v_add_u32_e32 v133, v103, v106
	ds_read_b128 v[28:31], v133
	ds_read_b128 v[32:35], v133 offset:64
	v_add_u32_e32 v131, v103, v107
	v_add_u32_e32 v132, v103, v108
	v_add_u32_e32 v85, v103, v109
	v_add_u32_e32 v87, v103, v110
	v_add_u32_e32 v127, v103, v111
	v_add_u32_e32 v128, v103, v112
	v_add_u32_e32 v129, v103, v113
	s_waitcnt lgkmcnt(1)
	v_mfma_f32_16x16x32_f16 v[28:31], v[28:31], v[60:63], 0
	v_add_u32_e32 v130, v103, v114
	s_or_b32 s20, s0, s8
	s_lshl_b64 s[12:13], s[20:21], 2
	s_waitcnt lgkmcnt(0)
	v_mfma_f32_16x16x32_f16 v[64:67], v[32:35], v[56:59], v[28:31]
	ds_read_b128 v[32:35], v131 offset:64
	s_add_u32 s12, s94, s12
	s_addc_u32 s13, s95, s13
	ds_read_b128 v[28:31], v131
	s_mov_b32 s5, 0xff800000
	s_mov_b32 s11, 0x3fb8aa3b
	s_waitcnt lgkmcnt(0)
	v_mfma_f32_16x16x32_f16 v[28:31], v[28:31], v[60:63], 0
	ds_read_b128 v[134:137], v129 offset:64
	v_mfma_f32_16x16x32_f16 v[52:55], v[32:35], v[56:59], v[28:31]
	ds_read_b128 v[32:35], v132 offset:64
	s_nop 4
	ds_read_b128 v[28:31], v132
	s_waitcnt lgkmcnt(0)
	v_mfma_f32_16x16x32_f16 v[28:31], v[28:31], v[60:63], 0
	v_mfma_f32_16x16x32_f16 v[48:51], v[32:35], v[56:59], v[28:31]
	ds_read_b128 v[32:35], v85 offset:64
	s_nop 5
	ds_read_b128 v[28:31], v85
	s_waitcnt lgkmcnt(0)
	v_mfma_f32_16x16x32_f16 v[28:31], v[28:31], v[60:63], 0
	v_mfma_f32_16x16x32_f16 v[44:47], v[32:35], v[56:59], v[28:31]
	ds_read_b128 v[32:35], v87 offset:64
	s_nop 5
	ds_read_b128 v[28:31], v87
	s_waitcnt lgkmcnt(0)
	v_mfma_f32_16x16x32_f16 v[28:31], v[28:31], v[60:63], 0
	v_mfma_f32_16x16x32_f16 v[40:43], v[32:35], v[56:59], v[28:31]
	ds_read_b128 v[32:35], v127 offset:64
	s_nop 5
	ds_read_b128 v[28:31], v127
	s_waitcnt lgkmcnt(0)
	v_mfma_f32_16x16x32_f16 v[28:31], v[28:31], v[60:63], 0
	v_mfma_f32_16x16x32_f16 v[36:39], v[32:35], v[56:59], v[28:31]
	ds_read_b128 v[32:35], v128 offset:64
	s_nop 5
	ds_read_b128 v[28:31], v128
	s_waitcnt lgkmcnt(0)
	v_mfma_f32_16x16x32_f16 v[28:31], v[28:31], v[60:63], 0
	v_mfma_f32_16x16x32_f16 v[32:35], v[32:35], v[56:59], v[28:31]
	s_nop 6
	ds_read_b128 v[28:31], v129
	s_waitcnt lgkmcnt(0)
	v_mfma_f32_16x16x32_f16 v[28:31], v[28:31], v[60:63], 0
	v_mfma_f32_16x16x32_f16 v[28:31], v[134:137], v[56:59], v[28:31]
	ds_read_b128 v[134:137], v130
	s_waitcnt lgkmcnt(0)
	v_mfma_f32_16x16x32_f16 v[60:63], v[134:137], v[60:63], 0
	ds_read_b128 v[134:137], v130 offset:64
	s_waitcnt lgkmcnt(0)
	v_mfma_f32_16x16x32_f16 v[56:59], v[134:137], v[56:59], v[60:63]
	s_nop 4
	s_waitcnt vmcnt(16)
	v_mov_b32_e32 v60, v170
	v_cndmask_b32_e64 v61, v187, v64, s[48:49]
	v_cndmask_b32_e64 v62, v187, v65, s[50:51]
	v_cndmask_b32_e64 v63, v187, v66, s[52:53]
	v_cndmask_b32_e64 v64, v187, v67, s[54:55]
	v_max3_f32 v65, v61, s5, v62
	v_max3_f32 v65, v65, v63, v64
	v_max3_f32 v65, v65, v52, v53
	v_max3_f32 v65, v65, v54, v55
	v_max3_f32 v65, v65, v48, v49
	v_max3_f32 v65, v65, v50, v51
	v_max3_f32 v65, v65, v44, v45
	v_max3_f32 v65, v65, v46, v47
	v_max3_f32 v65, v65, v40, v41
	v_max3_f32 v65, v65, v42, v43
	v_max3_f32 v65, v65, v36, v37
	v_max3_f32 v65, v65, v38, v39
	v_max3_f32 v65, v65, v32, v33
	v_max3_f32 v65, v65, v34, v35
	v_max3_f32 v65, v65, v28, v29
	v_cndmask_b32_e64 v56, v56, v187, s[48:49]
	v_cndmask_b32_e64 v57, v57, v187, s[50:51]
	v_max3_f32 v65, v65, v30, v31
	v_cndmask_b32_e64 v58, v58, v187, s[52:53]
	v_cndmask_b32_e64 v59, v59, v187, s[54:55]
	v_max3_f32 v65, v65, v56, v57
	v_max3_f32 v65, v65, v58, v59
	ds_bpermute_b32 v67, v104, v65
	s_waitcnt lgkmcnt(0)
	v_max_f32_e32 v67, v67, v67
	v_max_f32_e32 v65, v65, v67
	ds_bpermute_b32 v67, v105, v65
	s_waitcnt lgkmcnt(0)
	v_max_f32_e32 v67, v67, v67
	v_max_f32_e32 v65, v65, v67
	v_mul_f32_e32 v65, 0x3e38aa3b, v65
	s_nop 0
	v_mul_f32_e32 v66, 0x3fb8aa3b, v60
	v_max_f32_e32 v65, v65, v66
	v_fma_f32 v61, v61, s44, -v65
	v_exp_f32_e32 v61, v61
	v_fma_f32 v62, v62, s44, -v65
	v_exp_f32_e32 v62, v62
	v_fma_f32 v63, v63, s44, -v65
	v_exp_f32_e32 v63, v63
	v_fma_f32 v64, v64, s44, -v65
	v_exp_f32_e32 v64, v64
	v_fma_f32 v52, v52, s44, -v65
	v_add_f32_e32 v66, 0, v61
	v_exp_f32_e32 v52, v52
	v_fma_f32 v53, v53, s44, -v65
	v_add_f32_e32 v66, v62, v66
	v_exp_f32_e32 v53, v53
	v_fma_f32 v54, v54, s44, -v65
	v_add_f32_e32 v66, v63, v66
	v_exp_f32_e32 v54, v54
	v_fma_f32 v55, v55, s44, -v65
	v_add_f32_e32 v66, v64, v66
	v_exp_f32_e32 v55, v55
	v_fma_f32 v48, v48, s44, -v65
	v_add_f32_e32 v66, v52, v66
	v_exp_f32_e32 v48, v48
	v_fma_f32 v49, v49, s44, -v65
	v_add_f32_e32 v66, v53, v66
	v_exp_f32_e32 v49, v49
	v_fma_f32 v50, v50, s44, -v65
	v_add_f32_e32 v66, v54, v66
	v_exp_f32_e32 v50, v50
	v_fma_f32 v51, v51, s44, -v65
	v_add_f32_e32 v66, v55, v66
	v_exp_f32_e32 v51, v51
	v_fma_f32 v44, v44, s44, -v65
	v_add_f32_e32 v66, v48, v66
	v_exp_f32_e32 v67, v44
	v_add_f32_e32 v66, v49, v66
	v_add_f32_e32 v66, v50, v66
	v_add_f32_e32 v66, v51, v66
	v_fma_f32 v45, v45, s44, -v65
	v_add_f32_e32 v44, v67, v66
	v_exp_f32_e32 v66, v45
	v_fma_f32 v45, v46, s44, -v65
	v_exp_f32_e32 v134, v45
	v_fma_f32 v45, v47, s44, -v65
	v_exp_f32_e32 v135, v45
	v_fma_f32 v40, v40, s44, -v65
	v_exp_f32_e32 v136, v40
	v_fma_f32 v41, v41, s44, -v65
	v_add_f32_e32 v44, v66, v44
	v_exp_f32_e32 v137, v41
	v_fma_f32 v41, v42, s44, -v65
	v_add_f32_e32 v44, v134, v44
	v_exp_f32_e32 v138, v41
	v_fma_f32 v41, v43, s44, -v65
	v_add_f32_e32 v44, v135, v44
	v_exp_f32_e32 v139, v41
	v_fma_f32 v36, v36, s44, -v65
	v_add_f32_e32 v40, v136, v44
	v_exp_f32_e32 v140, v36
	v_fma_f32 v37, v37, s44, -v65
	v_add_f32_e32 v40, v137, v40
	v_exp_f32_e32 v141, v37
	v_fma_f32 v37, v38, s44, -v65
	v_add_f32_e32 v40, v138, v40
	v_exp_f32_e32 v142, v37
	v_fma_f32 v37, v39, s44, -v65
; #define LAS __attribute__((address_space(3)))
; __device__ __forceinline__ float shx(float v, int lane, int m) { return __builtin_bit_cast(float, __builtin_amdgcn_ds_bpermute((lane ^ m) << 2, __builtin_bit_cast(int, v))); }
; __device__ __forceinline__ float ex2(float x) { return __builtin_amdgcn_exp2f(x); }
; __device__ __forceinline__ h4 tr_read(const LAS half_t* p) { s4v r = __builtin_amdgcn_ds_read_tr16_b64_v4i16((LAS s4v*)p); return __builtin_bit_cast(h4, r); }
; template <bool FIRST>
; __device__ __forceinline__ void swa_item(const Params& p, int l, LAS unsigned char* lds, int item, int tid, int wave, int lane) {
;     ...
;         float ls = 0.f;
; #pragma unroll
;         for (int t = 0; t < 9; ++t)
; #pragma unroll
;             for (int e = 0; e < 4; ++e) { const float pv = ex2(__builtin_fmaf(s[t][e], SC2, -m)); s[t][e] = pv; ls += pv; }
;         ls += shx(ls, lane, 16); ls += shx(ls, lane, 32);
;         ls += ex2(sink2 - m);
;         const float inv = __builtin_amdgcn_rcpf(ls);
;         f32x4 o[4];
; #pragma unroll
;         for (int i = 0; i < 4; ++i) o[i] = (f32x4){0.f, 0.f, 0.f, 0.f};
; #pragma unroll
;         for (int pr = 0; pr < 5; ++pr) {
;             h8 bp;
; #pragma unroll
;             for (int e = 0; e < 4; ++e) { bp[e] = (half_t)s[2 * pr][e]; bp[4 + e] = (pr < 4) ? (half_t)s[(pr < 4) ? 2 * pr + 1 : 0][e] : (half_t)0.f; }
; #pragma unroll
;             for (int mt = 0; mt < 4; ++mt) { const LAS half_t* vp = Vs + ((wave + 2 * pr) * 16 + 4 * g + q) * SSTR + mt * 16 + 4 * pp;
;                 const h8 af = cat8(tr_read(vp), tr_read(vp + 16 * SSTR));
;                 o[mt] = __builtin_amdgcn_mfma_f32_16x16x32_f16(af, bp, o[mt], 0, 0, 0); }
;         }
	v_add_f32_e32 v40, v139, v40
	v_exp_f32_e32 v143, v37
	v_fma_f32 v32, v32, s44, -v65
	v_add_f32_e32 v36, v140, v40
	v_exp_f32_e32 v144, v32
	v_fma_f32 v33, v33, s44, -v65
	v_add_f32_e32 v36, v141, v36
	v_exp_f32_e32 v145, v33
	v_fma_f32 v33, v34, s44, -v65
	v_add_f32_e32 v36, v142, v36
	v_exp_f32_e32 v146, v33
	v_fma_f32 v33, v35, s44, -v65
	v_add_f32_e32 v36, v143, v36
	v_exp_f32_e32 v147, v33
	v_fma_f32 v28, v28, s44, -v65
	v_add_f32_e32 v32, v144, v36
	v_exp_f32_e32 v157, v28
	v_fma_f32 v29, v29, s44, -v65
	v_add_f32_e32 v32, v145, v32
	v_exp_f32_e32 v162, v29
	v_fma_f32 v29, v30, s44, -v65
	v_add_f32_e32 v32, v146, v32
	v_exp_f32_e32 v163, v29
	v_fma_f32 v29, v31, s44, -v65
	v_add_f32_e32 v32, v147, v32
	v_exp_f32_e32 v164, v29
	v_fma_f32 v29, v56, s44, -v65
	v_add_f32_e32 v28, v157, v32
	v_exp_f32_e32 v56, v29
	v_fma_f32 v29, v57, s44, -v65
	v_add_f32_e32 v28, v162, v28
	v_exp_f32_e32 v57, v29
	v_fma_f32 v29, v58, s44, -v65
	v_add_f32_e32 v28, v163, v28
	v_exp_f32_e32 v58, v29
	v_fma_f32 v29, v59, s44, -v65
	v_add_f32_e32 v28, v164, v28
	v_exp_f32_e32 v59, v29
	v_add_f32_e32 v28, v56, v28
	v_add_f32_e32 v28, v57, v28
	v_add_f32_e32 v28, v58, v28
	v_add_f32_e32 v28, v59, v28
	ds_bpermute_b32 v29, v104, v28
	ds_read_b64_tr_b16 v[34:35], v115 offset:41472
	ds_read_b64_tr_b16 v[32:33], v115 offset:39168
	ds_read_b64_tr_b16 v[36:37], v115 offset:39200
	ds_read_b64_tr_b16 v[38:39], v115 offset:41504
	ds_read_b64_tr_b16 v[40:41], v115 offset:39232
	ds_read_b64_tr_b16 v[42:43], v115 offset:41536
	ds_read_b64_tr_b16 v[44:45], v115 offset:39264
	ds_read_b64_tr_b16 v[46:47], v115 offset:41568
	s_waitcnt lgkmcnt(8)
	v_add_f32_e32 v28, v28, v29
	ds_bpermute_b32 v29, v105, v28
	v_cvt_pk_f16_f32 v31, v54, v55
	v_cvt_pk_f16_f32 v30, v52, v53
	s_waitcnt lgkmcnt(0)
	v_add_f32_e32 v28, v28, v29
	v_fma_f32 v29, v60, s11, -v65
	v_exp_f32_e32 v29, v29
	s_nop 0
	v_add_f32_e32 v60, v29, v28
	v_cvt_pk_f16_f32 v29, v63, v64
	v_cvt_pk_f16_f32 v28, v61, v62
	s_nop 1
	v_mfma_f32_16x16x32_f16 v[32:35], v[32:35], v[28:31], 0
	v_mfma_f32_16x16x32_f16 v[36:39], v[36:39], v[28:31], 0
	v_mfma_f32_16x16x32_f16 v[40:43], v[40:43], v[28:31], 0
	v_mfma_f32_16x16x32_f16 v[28:31], v[44:47], v[28:31], 0
	v_cvt_pk_f16_f32 v45, v50, v51
	v_cvt_pk_f16_f32 v44, v48, v49
	ds_read_b64_tr_b16 v[48:49], v115 offset:43776
	ds_read_b64_tr_b16 v[50:51], v115 offset:46080
	v_cvt_pk_f16_f32 v47, v134, v135
	v_cvt_pk_f16_f32 v46, v67, v66
	s_waitcnt lgkmcnt(0)
	s_nop 0
	v_mfma_f32_16x16x32_f16 v[32:35], v[48:51], v[44:47], v[32:35]
	ds_read_b64_tr_b16 v[48:49], v115 offset:43808
	ds_read_b64_tr_b16 v[50:51], v115 offset:46112
	s_waitcnt lgkmcnt(0)
	v_mfma_f32_16x16x32_f16 v[36:39], v[48:51], v[44:47], v[36:39]
	ds_read_b64_tr_b16 v[48:49], v115 offset:43840
	ds_read_b64_tr_b16 v[50:51], v115 offset:46144
	s_waitcnt lgkmcnt(0)
	v_mfma_f32_16x16x32_f16 v[40:43], v[48:51], v[44:47], v[40:43]
	ds_read_b64_tr_b16 v[48:49], v115 offset:43872
	ds_read_b64_tr_b16 v[50:51], v115 offset:46176
	s_waitcnt lgkmcnt(0)
	v_mfma_f32_16x16x32_f16 v[28:31], v[48:51], v[44:47], v[28:31]
	ds_read_b64_tr_b16 v[48:49], v115 offset:48384
	ds_read_b64_tr_b16 v[50:51], v115 offset:50688
	v_cvt_pk_f16_f32 v47, v142, v143
	v_cvt_pk_f16_f32 v46, v140, v141
	v_cvt_pk_f16_f32 v45, v138, v139
	v_cvt_pk_f16_f32 v44, v136, v137
	s_waitcnt lgkmcnt(0)
	s_nop 0
	v_mfma_f32_16x16x32_f16 v[32:35], v[48:51], v[44:47], v[32:35]
	ds_read_b64_tr_b16 v[48:49], v115 offset:48416
	ds_read_b64_tr_b16 v[50:51], v115 offset:50720
	s_waitcnt lgkmcnt(0)
	v_mfma_f32_16x16x32_f16 v[36:39], v[48:51], v[44:47], v[36:39]
	ds_read_b64_tr_b16 v[48:49], v115 offset:48448
	ds_read_b64_tr_b16 v[50:51], v115 offset:50752
	s_waitcnt lgkmcnt(0)
	v_mfma_f32_16x16x32_f16 v[40:43], v[48:51], v[44:47], v[40:43]
	ds_read_b64_tr_b16 v[48:49], v115 offset:48480
	ds_read_b64_tr_b16 v[50:51], v115 offset:50784
	s_waitcnt lgkmcnt(0)
	v_mfma_f32_16x16x32_f16 v[28:31], v[48:51], v[44:47], v[28:31]
	ds_read_b64_tr_b16 v[48:49], v115 offset:52992
	ds_read_b64_tr_b16 v[50:51], v115 offset:55296
	v_cvt_pk_f16_f32 v47, v163, v164
	v_cvt_pk_f16_f32 v46, v157, v162
	v_cvt_pk_f16_f32 v45, v146, v147
	v_cvt_pk_f16_f32 v44, v144, v145
	s_waitcnt lgkmcnt(0)
	s_nop 0
	v_mfma_f32_16x16x32_f16 v[32:35], v[48:51], v[44:47], v[32:35]
	ds_read_b64_tr_b16 v[48:49], v115 offset:53024
	ds_read_b64_tr_b16 v[50:51], v115 offset:55328
	s_waitcnt lgkmcnt(0)
	v_mfma_f32_16x16x32_f16 v[36:39], v[48:51], v[44:47], v[36:39]
	ds_read_b64_tr_b16 v[48:49], v115 offset:53056
	ds_read_b64_tr_b16 v[50:51], v115 offset:55360
	s_waitcnt lgkmcnt(0)
	v_mfma_f32_16x16x32_f16 v[48:51], v[48:51], v[44:47], v[40:43]
	s_nop 2
	ds_read_b64_tr_b16 v[40:41], v115 offset:53088
	ds_read_b64_tr_b16 v[42:43], v115 offset:55392
	s_waitcnt lgkmcnt(0)
	v_mfma_f32_16x16x32_f16 v[28:31], v[40:43], v[44:47], v[28:31]
	ds_read_b64_tr_b16 v[40:41], v115 offset:57600
	ds_read_b64_tr_b16 v[42:43], v115 offset:59904
	v_cvt_pk_f16_f32 v45, v58, v59
	v_cvt_pk_f16_f32 v44, v56, v57
	v_mov_b32_e32 v46, v3
	v_mov_b32_e32 v47, v3
	s_waitcnt lgkmcnt(0)
	s_nop 0
	v_mfma_f32_16x16x32_f16 v[40:43], v[40:43], v[44:47], v[32:35]
	s_nop 2
	ds_read_b64_tr_b16 v[32:33], v115 offset:57632
	ds_read_b64_tr_b16 v[34:35], v115 offset:59936
	s_waitcnt lgkmcnt(0)
	v_mfma_f32_16x16x32_f16 v[36:39], v[32:35], v[44:47], v[36:39]
	ds_read_b64_tr_b16 v[32:33], v115 offset:57664
	ds_read_b64_tr_b16 v[34:35], v115 offset:59968
	s_waitcnt lgkmcnt(0)
	v_mfma_f32_16x16x32_f16 v[32:35], v[32:35], v[44:47], v[48:51]
	s_nop 2
	ds_read_b64_tr_b16 v[48:49], v115 offset:57696
	ds_read_b64_tr_b16 v[50:51], v115 offset:60000
	s_waitcnt lgkmcnt(0)
; #define LAS __attribute__((address_space(3)))
; __device__ __forceinline__ float siluf(float x) { return x * __builtin_amdgcn_rcpf(1.f + ex2(x * -1.44269504f)); }
; template <bool FIRST>
; __device__ __forceinline__ void swa_item(const Params& p, int l, LAS unsigned char* lds, int item, int tid, int wave, int lane) {
;     ...
;         for (int t = 0; t < 9; ++t) { s[t] = (f32x4){0.f, 0.f, 0.f, 0.f};
; #pragma unroll
;             for (int ks = 0; ks < 2; ++ks) { const h8 a = *(const LAS h8*)(Ks + ((wave + t) * 16 + r) * SSTR + ks * 32 + g * 8);
;                 s[t] = __builtin_amdgcn_mfma_f32_16x16x32_f16(a, qf[ks], s[t], 0, 0, 0); } }
;     ...
; #pragma unroll
;         for (int mt = 0; mt < 4; ++mt) { const int col = hq * 64 + mt * 16 + 4 * g;
;             const h4 sg = *(const h4*)(PR + (size_t)tok * NIN + C_SG + col);
;             h4 y;
; #pragma unroll
;             for (int e = 0; e < 4; ++e) y[e] = op16(o[mt][e] * inv * siluf((float)sg[e]), TAIL_BF16);
;             *(h4*)(RA + (size_t)tok * 4096 + 2048 + col) = y; }
	v_mfma_f32_16x16x32_f16 v[28:31], v[48:51], v[44:47], v[28:31]
	v_or_b32_e32 v45, s4, v99
	v_lshlrev_b32_e32 v46, 1, v45
	v_lshl_add_u64 v[48:49], v[88:89], 0, v[46:47]
	s_waitcnt vmcnt(0)
	v_mov_b32_e32 v48, v192
	v_rcp_f32_e32 v44, v60
	v_mov_b32_e32 v49, v193
	v_cvt_f32_f16_e32 v50, v48
	v_cvt_f32_f16_sdwa v51, v48 dst_sel:DWORD dst_unused:UNUSED_PAD src0_sel:WORD_1
	v_cvt_f32_f16_e32 v48, v49
	v_cvt_f32_f16_sdwa v49, v49 dst_sel:DWORD dst_unused:UNUSED_PAD src0_sel:WORD_1
	v_mul_f32_e32 v45, 0xbfb8aa3b, v50
	v_exp_f32_e32 v45, v45
	s_nop 0
	v_add_f32_e32 v45, 1.0, v45
	v_rcp_f32_e32 v52, v45
	v_pk_mul_f32 v[40:41], v[44:45], v[40:41] op_sel_hi:[0,1]
	v_mul_f32_e32 v45, 0xbfb8aa3b, v51
	v_exp_f32_e32 v45, v45
	s_nop 0
	v_add_f32_e32 v45, 1.0, v45
	v_rcp_f32_e32 v53, v45
	v_pk_mul_f32 v[42:43], v[44:45], v[42:43] op_sel_hi:[0,1]
	v_pk_mul_f32 v[36:37], v[44:45], v[36:37] op_sel_hi:[0,1]
	v_pk_mul_f32 v[38:39], v[44:45], v[38:39] op_sel_hi:[0,1]
	v_pk_mul_f32 v[50:51], v[52:53], v[50:51]
	v_pk_mul_f32 v[32:33], v[44:45], v[32:33] op_sel_hi:[0,1]
	v_pk_mul_f32 v[40:41], v[40:41], v[50:51]
	v_pk_mul_f32 v[34:35], v[44:45], v[34:35] op_sel_hi:[0,1]
	v_cvt_pk_bf16_f32 v40, v40, v41
	v_mul_f32_e32 v41, 0xbfb8aa3b, v48
	v_exp_f32_e32 v41, v41
	v_pk_mul_f32 v[28:29], v[44:45], v[28:29] op_sel_hi:[0,1]
	v_pk_mul_f32 v[30:31], v[44:45], v[30:31] op_sel_hi:[0,1]
	v_add_f32_e32 v41, 1.0, v41
	v_rcp_f32_e32 v50, v41
	v_mul_f32_e32 v41, 0xbfb8aa3b, v49
	v_exp_f32_e32 v41, v41
	s_nop 0
	v_add_f32_e32 v41, 1.0, v41
	v_rcp_f32_e32 v51, v41
	s_nop 0
	v_pk_mul_f32 v[48:49], v[50:51], v[48:49]
	s_nop 0
	v_pk_mul_f32 v[42:43], v[42:43], v[48:49]
	s_nop 0
	v_cvt_pk_bf16_f32 v41, v42, v43
	v_lshl_add_u64 v[42:43], v[0:1], 0, v[46:47]
	global_store_dwordx2 v[42:43], v[40:41], off
	v_or_b32_e32 v40, 32, v46
	v_mov_b32_e32 v41, v3
	v_lshl_add_u64 v[42:43], v[88:89], 0, v[40:41]
	v_mov_b32_e32 v42, v194
	v_mov_b32_e32 v43, v195
	v_cvt_f32_f16_e32 v48, v42
	v_cvt_f32_f16_sdwa v49, v42 dst_sel:DWORD dst_unused:UNUSED_PAD src0_sel:WORD_1
	v_mul_f32_e32 v42, 0xbfb8aa3b, v48
	v_exp_f32_e32 v42, v42
	s_nop 0
	v_add_f32_e32 v42, 1.0, v42
	v_rcp_f32_e32 v50, v42
	v_mul_f32_e32 v42, 0xbfb8aa3b, v49
	v_exp_f32_e32 v42, v42
	s_nop 0
	v_add_f32_e32 v42, 1.0, v42
	v_rcp_f32_e32 v51, v42
	v_cvt_f32_f16_e32 v42, v43
	v_cvt_f32_f16_sdwa v43, v43 dst_sel:DWORD dst_unused:UNUSED_PAD src0_sel:WORD_1
	v_pk_mul_f32 v[48:49], v[50:51], v[48:49]
	s_nop 0
	v_pk_mul_f32 v[36:37], v[36:37], v[48:49]
	s_nop 0
	v_cvt_pk_bf16_f32 v36, v36, v37
	v_mul_f32_e32 v37, 0xbfb8aa3b, v42
	v_exp_f32_e32 v37, v37
	s_nop 0
	v_add_f32_e32 v37, 1.0, v37
	v_rcp_f32_e32 v48, v37
	v_mul_f32_e32 v37, 0xbfb8aa3b, v43
	v_exp_f32_e32 v37, v37
	s_nop 0
	v_add_f32_e32 v37, 1.0, v37
	v_rcp_f32_e32 v49, v37
	s_nop 0
	v_pk_mul_f32 v[42:43], v[48:49], v[42:43]
	s_nop 0
	v_pk_mul_f32 v[38:39], v[38:39], v[42:43]
	s_nop 0
	v_cvt_pk_bf16_f32 v37, v38, v39
	v_lshl_add_u64 v[38:39], v[0:1], 0, v[40:41]
	global_store_dwordx2 v[38:39], v[36:37], off
	v_or_b32_e32 v36, 64, v46
	v_mov_b32_e32 v37, v3
	v_lshl_add_u64 v[38:39], v[88:89], 0, v[36:37]
	v_mov_b32_e32 v38, v196
	v_mov_b32_e32 v39, v197
	v_cvt_f32_f16_e32 v40, v38
	v_cvt_f32_f16_sdwa v41, v38 dst_sel:DWORD dst_unused:UNUSED_PAD src0_sel:WORD_1
	v_mul_f32_e32 v38, 0xbfb8aa3b, v40
	v_exp_f32_e32 v38, v38
	s_nop 0
	v_add_f32_e32 v38, 1.0, v38
	v_rcp_f32_e32 v42, v38
	v_mul_f32_e32 v38, 0xbfb8aa3b, v41
	v_exp_f32_e32 v38, v38
	s_nop 0
	v_add_f32_e32 v38, 1.0, v38
	v_rcp_f32_e32 v43, v38
	v_cvt_f32_f16_e32 v38, v39
	v_cvt_f32_f16_sdwa v39, v39 dst_sel:DWORD dst_unused:UNUSED_PAD src0_sel:WORD_1
	v_pk_mul_f32 v[40:41], v[42:43], v[40:41]
	s_nop 0
	v_pk_mul_f32 v[32:33], v[32:33], v[40:41]
	s_nop 0
	v_cvt_pk_bf16_f32 v32, v32, v33
	v_mul_f32_e32 v33, 0xbfb8aa3b, v38
	v_exp_f32_e32 v33, v33
	s_nop 0
	v_add_f32_e32 v33, 1.0, v33
	v_rcp_f32_e32 v40, v33
	v_mul_f32_e32 v33, 0xbfb8aa3b, v39
	v_exp_f32_e32 v33, v33
	s_nop 0
	v_add_f32_e32 v33, 1.0, v33
	v_rcp_f32_e32 v41, v33
	s_nop 0
	v_pk_mul_f32 v[38:39], v[40:41], v[38:39]
	s_nop 0
	v_pk_mul_f32 v[34:35], v[34:35], v[38:39]
	s_nop 0
	v_cvt_pk_bf16_f32 v33, v34, v35
	v_lshl_add_u64 v[34:35], v[0:1], 0, v[36:37]
	global_store_dwordx2 v[34:35], v[32:33], off
	v_or_b32_e32 v32, 0x60, v46
	v_mov_b32_e32 v33, v3
	v_lshl_add_u64 v[34:35], v[88:89], 0, v[32:33]
	v_mov_b32_e32 v34, v198
	v_mov_b32_e32 v35, v199
	v_cvt_f32_f16_e32 v36, v34
	v_cvt_f32_f16_sdwa v37, v34 dst_sel:DWORD dst_unused:UNUSED_PAD src0_sel:WORD_1
	v_mul_f32_e32 v34, 0xbfb8aa3b, v36
	v_exp_f32_e32 v34, v34
	s_nop 0
	v_add_f32_e32 v34, 1.0, v34
	v_rcp_f32_e32 v38, v34
	v_mul_f32_e32 v34, 0xbfb8aa3b, v37
	v_exp_f32_e32 v34, v34
	s_nop 0
	v_add_f32_e32 v34, 1.0, v34
	v_rcp_f32_e32 v39, v34
	v_cvt_f32_f16_e32 v34, v35
	v_cvt_f32_f16_sdwa v35, v35 dst_sel:DWORD dst_unused:UNUSED_PAD src0_sel:WORD_1
	v_pk_mul_f32 v[36:37], v[38:39], v[36:37]
	s_nop 0
	v_pk_mul_f32 v[28:29], v[28:29], v[36:37]
	s_nop 0
	v_cvt_pk_bf16_f32 v28, v28, v29
	v_mul_f32_e32 v29, 0xbfb8aa3b, v34
	v_exp_f32_e32 v29, v29
	s_nop 0
	v_add_f32_e32 v29, 1.0, v29
	v_rcp_f32_e32 v36, v29
	v_mul_f32_e32 v29, 0xbfb8aa3b, v35
	v_exp_f32_e32 v29, v29
	s_nop 0
	v_add_f32_e32 v29, 1.0, v29
	v_rcp_f32_e32 v37, v29
	s_nop 0
	v_pk_mul_f32 v[34:35], v[36:37], v[34:35]
	s_nop 0
	v_pk_mul_f32 v[30:31], v[30:31], v[34:35]
	s_nop 0
	v_cvt_pk_bf16_f32 v29, v30, v31
	v_lshl_add_u64 v[30:31], v[0:1], 0, v[32:33]
	global_store_dwordx2 v[30:31], v[28:29], off
	ds_read_b128 v[28:31], v133
	ds_read_b128 v[32:35], v133 offset:64
	s_add_i32 s20, s0, s8
	s_lshl_b64 s[0:1], s[20:21], 2
	s_add_u32 s0, s94, s0
	s_addc_u32 s1, s95, s1
	s_waitcnt lgkmcnt(1)
; #define LAS __attribute__((address_space(3)))
; __device__ __forceinline__ float shx(float v, int lane, int m) { return __builtin_bit_cast(float, __builtin_amdgcn_ds_bpermute((lane ^ m) << 2, __builtin_bit_cast(int, v))); }
; __device__ __forceinline__ float ex2(float x) { return __builtin_amdgcn_exp2f(x); }
; template <bool FIRST>
; __device__ __forceinline__ void swa_item(const Params& p, int l, LAS unsigned char* lds, int item, int tid, int wave, int lane) {
;     ...
;         for (int t = 0; t < 9; ++t) { s[t] = (f32x4){0.f, 0.f, 0.f, 0.f};
; #pragma unroll
;             for (int ks = 0; ks < 2; ++ks) { const h8 a = *(const LAS h8*)(Ks + ((wave + t) * 16 + r) * SSTR + ks * 32 + g * 8);
;                 s[t] = __builtin_amdgcn_mfma_f32_16x16x32_f16(a, qf[ks], s[t], 0, 0, 0); } }
;         const float SC2 = 0.125f * 1.44269504f;
;         const float sink2 = p.sinks[l * 32 + hq] * 1.44269504f;
;         const int rg4 = r - 4 * g;
; #pragma unroll
;         for (int e = 0; e < 4; ++e) { s[0][e] = (rg4 < e) ? s[0][e] : -INFINITY; s[8][e] = (rg4 >= e) ? s[8][e] : -INFINITY; }
;         if (FIRST) {
; #pragma unroll
;             for (int t = 0; t < 9; ++t) { const bool tile_ok = (wave + t >= 8);
; #pragma unroll
;                 for (int e = 0; e < 4; ++e) s[t][e] = tile_ok ? s[t][e] : -INFINITY; }
;         }
;         float mr = -INFINITY;
; #pragma unroll
;         for (int t = 0; t < 9; ++t)
; #pragma unroll
;             for (int e = 0; e < 4; ++e) mr = fmaxf(mr, s[t][e]);
;         mr = fmaxf(mr, shx(mr, lane, 16)); mr = fmaxf(mr, shx(mr, lane, 32));
;         const float m = fmaxf(mr * SC2, sink2);
;         float ls = 0.f;
; #pragma unroll
;         for (int t = 0; t < 9; ++t)
; #pragma unroll
;             for (int e = 0; e < 4; ++e) { const float pv = ex2(__builtin_fmaf(s[t][e], SC2, -m)); s[t][e] = pv; ls += pv; }
;         ls += shx(ls, lane, 16); ls += shx(ls, lane, 32);
	v_mfma_f32_16x16x32_f16 v[28:31], v[28:31], v[24:27], 0
	ds_read_b128 v[60:63], v129 offset:64
	s_waitcnt lgkmcnt(1)
	v_mfma_f32_16x16x32_f16 v[56:59], v[32:35], v[20:23], v[28:31]
	ds_read_b128 v[32:35], v131 offset:64
	s_nop 3
	ds_read_b128 v[28:31], v131
	s_waitcnt lgkmcnt(0)
	v_mfma_f32_16x16x32_f16 v[28:31], v[28:31], v[24:27], 0
	v_mfma_f32_16x16x32_f16 v[52:55], v[32:35], v[20:23], v[28:31]
	ds_read_b128 v[32:35], v132 offset:64
	s_nop 5
	ds_read_b128 v[28:31], v132
	s_waitcnt lgkmcnt(0)
	v_mfma_f32_16x16x32_f16 v[28:31], v[28:31], v[24:27], 0
	v_mfma_f32_16x16x32_f16 v[48:51], v[32:35], v[20:23], v[28:31]
	ds_read_b128 v[32:35], v85 offset:64
	s_nop 5
	ds_read_b128 v[28:31], v85
	s_waitcnt lgkmcnt(0)
	v_mfma_f32_16x16x32_f16 v[28:31], v[28:31], v[24:27], 0
	v_mfma_f32_16x16x32_f16 v[44:47], v[32:35], v[20:23], v[28:31]
	ds_read_b128 v[32:35], v87 offset:64
	s_nop 5
	ds_read_b128 v[28:31], v87
	s_waitcnt lgkmcnt(0)
	v_mfma_f32_16x16x32_f16 v[28:31], v[28:31], v[24:27], 0
	v_mfma_f32_16x16x32_f16 v[40:43], v[32:35], v[20:23], v[28:31]
	ds_read_b128 v[32:35], v127 offset:64
	s_nop 5
	ds_read_b128 v[28:31], v127
	s_waitcnt lgkmcnt(0)
	v_mfma_f32_16x16x32_f16 v[28:31], v[28:31], v[24:27], 0
	v_mfma_f32_16x16x32_f16 v[36:39], v[32:35], v[20:23], v[28:31]
	ds_read_b128 v[32:35], v128 offset:64
	s_nop 5
	ds_read_b128 v[28:31], v128
	s_waitcnt lgkmcnt(0)
	v_mfma_f32_16x16x32_f16 v[28:31], v[28:31], v[24:27], 0
	v_mfma_f32_16x16x32_f16 v[32:35], v[32:35], v[20:23], v[28:31]
	s_nop 6
	ds_read_b128 v[28:31], v129
	s_waitcnt lgkmcnt(0)
	v_mfma_f32_16x16x32_f16 v[28:31], v[28:31], v[24:27], 0
	v_mfma_f32_16x16x32_f16 v[28:31], v[60:63], v[20:23], v[28:31]
	ds_read_b128 v[60:63], v130
	s_waitcnt lgkmcnt(0)
	v_mfma_f32_16x16x32_f16 v[24:27], v[60:63], v[24:27], 0
	ds_read_b128 v[60:63], v130 offset:64
	s_waitcnt lgkmcnt(0)
	v_mfma_f32_16x16x32_f16 v[20:23], v[60:63], v[20:23], v[24:27]
	s_nop 4
	v_mov_b32_e32 v24, v171
	v_cndmask_b32_e64 v25, v187, v56, s[48:49]
	v_cndmask_b32_e64 v26, v187, v57, s[50:51]
	v_cndmask_b32_e64 v27, v187, v58, s[52:53]
	v_cndmask_b32_e64 v56, v187, v59, s[54:55]
	v_max3_f32 v57, v25, s5, v26
	v_max3_f32 v57, v57, v27, v56
	v_max3_f32 v57, v57, v52, v53
	v_max3_f32 v57, v57, v54, v55
	v_max3_f32 v57, v57, v48, v49
	v_max3_f32 v57, v57, v50, v51
	v_max3_f32 v57, v57, v44, v45
	v_max3_f32 v57, v57, v46, v47
	v_max3_f32 v57, v57, v40, v41
	v_max3_f32 v57, v57, v42, v43
	v_max3_f32 v57, v57, v36, v37
	v_max3_f32 v57, v57, v38, v39
	v_max3_f32 v57, v57, v32, v33
	v_max3_f32 v57, v57, v34, v35
	v_max3_f32 v57, v57, v28, v29
	v_cndmask_b32_e64 v20, v20, v187, s[48:49]
	v_cndmask_b32_e64 v21, v21, v187, s[50:51]
	v_max3_f32 v57, v57, v30, v31
	v_cndmask_b32_e64 v22, v22, v187, s[52:53]
	v_cndmask_b32_e64 v23, v23, v187, s[54:55]
	v_max3_f32 v57, v57, v20, v21
	v_max3_f32 v57, v57, v22, v23
	ds_bpermute_b32 v59, v104, v57
	s_waitcnt lgkmcnt(0)
	v_max_f32_e32 v59, v59, v59
	v_max_f32_e32 v57, v57, v59
	ds_bpermute_b32 v59, v105, v57
	s_waitcnt lgkmcnt(0)
	v_max_f32_e32 v59, v59, v59
	v_max_f32_e32 v57, v57, v59
	v_mul_f32_e32 v57, 0x3e38aa3b, v57
	s_nop 0
	v_mul_f32_e32 v58, 0x3fb8aa3b, v24
	v_max_f32_e32 v57, v57, v58
	v_fma_f32 v25, v25, s44, -v57
	v_exp_f32_e32 v25, v25
	v_fma_f32 v26, v26, s44, -v57
	v_exp_f32_e32 v26, v26
	v_fma_f32 v27, v27, s44, -v57
	v_exp_f32_e32 v27, v27
	v_fma_f32 v56, v56, s44, -v57
	v_exp_f32_e32 v56, v56
	v_fma_f32 v52, v52, s44, -v57
	v_add_f32_e32 v58, 0, v25
	v_exp_f32_e32 v52, v52
	v_fma_f32 v53, v53, s44, -v57
	v_add_f32_e32 v58, v26, v58
	v_exp_f32_e32 v53, v53
	v_fma_f32 v54, v54, s44, -v57
	v_add_f32_e32 v58, v27, v58
	v_exp_f32_e32 v54, v54
	v_fma_f32 v55, v55, s44, -v57
	v_add_f32_e32 v58, v56, v58
	v_exp_f32_e32 v55, v55
	v_fma_f32 v48, v48, s44, -v57
	v_add_f32_e32 v58, v52, v58
	v_exp_f32_e32 v48, v48
	v_fma_f32 v49, v49, s44, -v57
	v_add_f32_e32 v58, v53, v58
	v_exp_f32_e32 v49, v49
	v_fma_f32 v50, v50, s44, -v57
	v_add_f32_e32 v58, v54, v58
	v_exp_f32_e32 v50, v50
	v_fma_f32 v51, v51, s44, -v57
	v_add_f32_e32 v58, v55, v58
	v_exp_f32_e32 v51, v51
	v_fma_f32 v44, v44, s44, -v57
	v_add_f32_e32 v58, v48, v58
	v_exp_f32_e32 v44, v44
	v_fma_f32 v45, v45, s44, -v57
	v_add_f32_e32 v58, v49, v58
	v_exp_f32_e32 v45, v45
	v_fma_f32 v46, v46, s44, -v57
	v_add_f32_e32 v58, v50, v58
	v_exp_f32_e32 v46, v46
	v_fma_f32 v47, v47, s44, -v57
	v_add_f32_e32 v58, v51, v58
	v_exp_f32_e32 v47, v47
	v_fma_f32 v40, v40, s44, -v57
	v_add_f32_e32 v58, v44, v58
	v_exp_f32_e32 v59, v40
	v_add_f32_e32 v58, v45, v58
	v_add_f32_e32 v58, v46, v58
	v_add_f32_e32 v58, v47, v58
	v_fma_f32 v41, v41, s44, -v57
	v_add_f32_e32 v40, v59, v58
	v_exp_f32_e32 v58, v41
	v_fma_f32 v41, v42, s44, -v57
	v_exp_f32_e32 v60, v41
	v_fma_f32 v41, v43, s44, -v57
	v_exp_f32_e32 v61, v41
	v_fma_f32 v36, v36, s44, -v57
	v_exp_f32_e32 v62, v36
	v_fma_f32 v37, v37, s44, -v57
	v_add_f32_e32 v40, v58, v40
	v_exp_f32_e32 v63, v37
	v_fma_f32 v37, v38, s44, -v57
	v_add_f32_e32 v40, v60, v40
	v_exp_f32_e32 v64, v37
	v_fma_f32 v37, v39, s44, -v57
	v_add_f32_e32 v40, v61, v40
	v_exp_f32_e32 v65, v37
	v_fma_f32 v32, v32, s44, -v57
	v_add_f32_e32 v36, v62, v40
	v_exp_f32_e32 v66, v32
	v_fma_f32 v33, v33, s44, -v57
	v_add_f32_e32 v36, v63, v36
	v_exp_f32_e32 v67, v33
	v_fma_f32 v33, v34, s44, -v57
	v_add_f32_e32 v36, v64, v36
	v_exp_f32_e32 v134, v33
	v_fma_f32 v33, v35, s44, -v57
	v_add_f32_e32 v36, v65, v36
	v_exp_f32_e32 v135, v33
	v_fma_f32 v28, v28, s44, -v57
	v_add_f32_e32 v32, v66, v36
	v_exp_f32_e32 v136, v28
	v_fma_f32 v29, v29, s44, -v57
	v_add_f32_e32 v32, v67, v32
	v_exp_f32_e32 v137, v29
	v_fma_f32 v29, v30, s44, -v57
	v_add_f32_e32 v32, v134, v32
	v_exp_f32_e32 v138, v29
	v_fma_f32 v29, v31, s44, -v57
	v_add_f32_e32 v32, v135, v32
	v_exp_f32_e32 v139, v29
	v_fma_f32 v20, v20, s44, -v57
	v_add_f32_e32 v28, v136, v32
	v_exp_f32_e32 v140, v20
	v_fma_f32 v21, v21, s44, -v57
	v_add_f32_e32 v28, v137, v28
	v_exp_f32_e32 v141, v21
	v_fma_f32 v21, v22, s44, -v57
	v_add_f32_e32 v28, v138, v28
	v_exp_f32_e32 v142, v21
	v_fma_f32 v21, v23, s44, -v57
	v_add_f32_e32 v28, v139, v28
	v_exp_f32_e32 v143, v21
	v_add_f32_e32 v20, v140, v28
	v_add_f32_e32 v20, v141, v20
	v_add_f32_e32 v20, v142, v20
	v_add_f32_e32 v20, v143, v20
	ds_bpermute_b32 v21, v104, v20
	v_cvt_pk_f16_f32 v23, v54, v55
	v_cvt_pk_f16_f32 v22, v52, v53
	s_waitcnt lgkmcnt(0)
; #define LAS __attribute__((address_space(3)))
; __device__ __forceinline__ float shx(float v, int lane, int m) { return __builtin_bit_cast(float, __builtin_amdgcn_ds_bpermute((lane ^ m) << 2, __builtin_bit_cast(int, v))); }
; __device__ __forceinline__ float ex2(float x) { return __builtin_amdgcn_exp2f(x); }
; __device__ __forceinline__ h4 tr_read(const LAS half_t* p) { s4v r = __builtin_amdgcn_ds_read_tr16_b64_v4i16((LAS s4v*)p); return __builtin_bit_cast(h4, r); }
; template <bool FIRST>
; __device__ __forceinline__ void swa_item(const Params& p, int l, LAS unsigned char* lds, int item, int tid, int wave, int lane) {
;     ...
;         ls += shx(ls, lane, 16); ls += shx(ls, lane, 32);
;         ls += ex2(sink2 - m);
;         const float inv = __builtin_amdgcn_rcpf(ls);
;         f32x4 o[4];
; #pragma unroll
;         for (int i = 0; i < 4; ++i) o[i] = (f32x4){0.f, 0.f, 0.f, 0.f};
; #pragma unroll
;         for (int pr = 0; pr < 5; ++pr) {
;             h8 bp;
; #pragma unroll
;             for (int e = 0; e < 4; ++e) { bp[e] = (half_t)s[2 * pr][e]; bp[4 + e] = (pr < 4) ? (half_t)s[(pr < 4) ? 2 * pr + 1 : 0][e] : (half_t)0.f; }
; #pragma unroll
;             for (int mt = 0; mt < 4; ++mt) { const LAS half_t* vp = Vs + ((wave + 2 * pr) * 16 + 4 * g + q) * SSTR + mt * 16 + 4 * pp;
;                 const h8 af = cat8(tr_read(vp), tr_read(vp + 16 * SSTR));
;                 o[mt] = __builtin_amdgcn_mfma_f32_16x16x32_f16(af, bp, o[mt], 0, 0, 0); }
;         }
	v_add_f32_e32 v20, v20, v21
	ds_bpermute_b32 v21, v105, v20
	s_waitcnt lgkmcnt(0)
	v_add_f32_e32 v20, v20, v21
	v_fma_f32 v21, v24, s11, -v57
	v_exp_f32_e32 v21, v21
	s_nop 0
	v_add_f32_e32 v57, v21, v20
	v_cvt_pk_f16_f32 v21, v27, v56
	v_cvt_pk_f16_f32 v20, v25, v26
	ds_read_b64_tr_b16 v[26:27], v115 offset:41472
	ds_read_b64_tr_b16 v[24:25], v115 offset:39168
	ds_read_b64_tr_b16 v[28:29], v115 offset:39200
	ds_read_b64_tr_b16 v[30:31], v115 offset:41504
	ds_read_b64_tr_b16 v[32:33], v115 offset:39232
	ds_read_b64_tr_b16 v[34:35], v115 offset:41536
	ds_read_b64_tr_b16 v[36:37], v115 offset:39264
	ds_read_b64_tr_b16 v[38:39], v115 offset:41568
	ds_read_b64_tr_b16 v[40:41], v115 offset:43776
	ds_read_b64_tr_b16 v[42:43], v115 offset:46080
	s_waitcnt lgkmcnt(8)
	v_mfma_f32_16x16x32_f16 v[24:27], v[24:27], v[20:23], 0
	s_waitcnt lgkmcnt(6)
	v_mfma_f32_16x16x32_f16 v[28:31], v[28:31], v[20:23], 0
	s_waitcnt lgkmcnt(4)
	v_mfma_f32_16x16x32_f16 v[32:35], v[32:35], v[20:23], 0
	s_waitcnt lgkmcnt(2)
	v_mfma_f32_16x16x32_f16 v[20:23], v[36:39], v[20:23], 0
	v_cvt_pk_f16_f32 v39, v46, v47
	v_cvt_pk_f16_f32 v38, v44, v45
	v_cvt_pk_f16_f32 v37, v50, v51
	v_cvt_pk_f16_f32 v36, v48, v49
	s_waitcnt lgkmcnt(0)
	s_nop 0
	v_mfma_f32_16x16x32_f16 v[24:27], v[40:43], v[36:39], v[24:27]
	ds_read_b64_tr_b16 v[40:41], v115 offset:43808
	ds_read_b64_tr_b16 v[42:43], v115 offset:46112
	s_waitcnt lgkmcnt(0)
	v_mfma_f32_16x16x32_f16 v[28:31], v[40:43], v[36:39], v[28:31]
	ds_read_b64_tr_b16 v[40:41], v115 offset:43840
	ds_read_b64_tr_b16 v[42:43], v115 offset:46144
	s_waitcnt lgkmcnt(0)
	v_mfma_f32_16x16x32_f16 v[32:35], v[40:43], v[36:39], v[32:35]
	ds_read_b64_tr_b16 v[40:41], v115 offset:43872
	ds_read_b64_tr_b16 v[42:43], v115 offset:46176
	s_waitcnt lgkmcnt(0)
	v_mfma_f32_16x16x32_f16 v[20:23], v[40:43], v[36:39], v[20:23]
	ds_read_b64_tr_b16 v[40:41], v115 offset:48384
	ds_read_b64_tr_b16 v[42:43], v115 offset:50688
	v_cvt_pk_f16_f32 v39, v64, v65
	v_cvt_pk_f16_f32 v38, v62, v63
	v_cvt_pk_f16_f32 v37, v60, v61
	v_cvt_pk_f16_f32 v36, v59, v58
	s_waitcnt lgkmcnt(0)
	s_nop 0
	v_mfma_f32_16x16x32_f16 v[24:27], v[40:43], v[36:39], v[24:27]
	ds_read_b64_tr_b16 v[40:41], v115 offset:48416
	ds_read_b64_tr_b16 v[42:43], v115 offset:50720
	s_waitcnt lgkmcnt(0)
	v_mfma_f32_16x16x32_f16 v[28:31], v[40:43], v[36:39], v[28:31]
	ds_read_b64_tr_b16 v[40:41], v115 offset:48448
	ds_read_b64_tr_b16 v[42:43], v115 offset:50752
	s_waitcnt lgkmcnt(0)
	v_mfma_f32_16x16x32_f16 v[32:35], v[40:43], v[36:39], v[32:35]
	ds_read_b64_tr_b16 v[40:41], v115 offset:48480
	ds_read_b64_tr_b16 v[42:43], v115 offset:50784
	s_waitcnt lgkmcnt(0)
	v_mfma_f32_16x16x32_f16 v[20:23], v[40:43], v[36:39], v[20:23]
	ds_read_b64_tr_b16 v[40:41], v115 offset:52992
	ds_read_b64_tr_b16 v[42:43], v115 offset:55296
	v_cvt_pk_f16_f32 v39, v138, v139
	v_cvt_pk_f16_f32 v38, v136, v137
	v_cvt_pk_f16_f32 v37, v134, v135
	v_cvt_pk_f16_f32 v36, v66, v67
	s_waitcnt lgkmcnt(0)
	s_nop 0
	v_mfma_f32_16x16x32_f16 v[24:27], v[40:43], v[36:39], v[24:27]
	ds_read_b64_tr_b16 v[40:41], v115 offset:53024
	ds_read_b64_tr_b16 v[42:43], v115 offset:55328
	s_waitcnt lgkmcnt(0)
	v_mfma_f32_16x16x32_f16 v[28:31], v[40:43], v[36:39], v[28:31]
	ds_read_b64_tr_b16 v[40:41], v115 offset:53056
	ds_read_b64_tr_b16 v[42:43], v115 offset:55360
	s_waitcnt lgkmcnt(0)
	v_mfma_f32_16x16x32_f16 v[40:43], v[40:43], v[36:39], v[32:35]
	s_nop 2
	ds_read_b64_tr_b16 v[32:33], v115 offset:53088
	ds_read_b64_tr_b16 v[34:35], v115 offset:55392
	s_waitcnt lgkmcnt(0)
	v_mfma_f32_16x16x32_f16 v[20:23], v[32:35], v[36:39], v[20:23]
	ds_read_b64_tr_b16 v[32:33], v115 offset:57600
	ds_read_b64_tr_b16 v[34:35], v115 offset:59904
	v_cvt_pk_f16_f32 v37, v142, v143
	v_cvt_pk_f16_f32 v36, v140, v141
	v_mov_b32_e32 v38, v3
	v_mov_b32_e32 v39, v3
	s_waitcnt lgkmcnt(0)
	s_nop 0
	v_mfma_f32_16x16x32_f16 v[32:35], v[32:35], v[36:39], v[24:27]
	s_nop 2
	ds_read_b64_tr_b16 v[24:25], v115 offset:57632
	ds_read_b64_tr_b16 v[26:27], v115 offset:59936
	s_waitcnt lgkmcnt(0)
	v_mfma_f32_16x16x32_f16 v[28:31], v[24:27], v[36:39], v[28:31]
	ds_read_b64_tr_b16 v[24:25], v115 offset:57664
	ds_read_b64_tr_b16 v[26:27], v115 offset:59968
	s_waitcnt lgkmcnt(0)
	v_mfma_f32_16x16x32_f16 v[24:27], v[24:27], v[36:39], v[40:43]
	s_nop 2
	ds_read_b64_tr_b16 v[40:41], v115 offset:57696
	ds_read_b64_tr_b16 v[42:43], v115 offset:60000
	s_waitcnt lgkmcnt(0)
; __device__ __forceinline__ float siluf(float x) { return x * __builtin_amdgcn_rcpf(1.f + ex2(x * -1.44269504f)); }
; template <bool FIRST>
; __device__ __forceinline__ void swa_item(const Params& p, int l, LAS unsigned char* lds, int item, int tid, int wave, int lane) {
;     ...
; #pragma unroll
;         for (int mt = 0; mt < 4; ++mt) { const int col = hq * 64 + mt * 16 + 4 * g;
;             const h4 sg = *(const h4*)(PR + (size_t)tok * NIN + C_SG + col);
;             h4 y;
; #pragma unroll
;             for (int e = 0; e < 4; ++e) y[e] = op16(o[mt][e] * inv * siluf((float)sg[e]), TAIL_BF16);
;             *(h4*)(RA + (size_t)tok * 4096 + 2048 + col) = y; }
	v_mfma_f32_16x16x32_f16 v[20:23], v[40:43], v[36:39], v[20:23]
	v_lshlrev_b32_e32 v37, 1, v99
	v_lshl_or_b32 v48, s10, 9, v37
	v_or_b32_e32 v38, 0x80, v48
	v_lshl_add_u64 v[40:41], v[88:89], 0, v[38:39]
	v_mov_b32_e32 v40, v200
	v_rcp_f32_e32 v36, v57
	v_mov_b32_e32 v41, v201
	v_cvt_f32_f16_e32 v42, v40
	v_cvt_f32_f16_sdwa v43, v40 dst_sel:DWORD dst_unused:UNUSED_PAD src0_sel:WORD_1
	v_cvt_f32_f16_e32 v40, v41
	v_cvt_f32_f16_sdwa v41, v41 dst_sel:DWORD dst_unused:UNUSED_PAD src0_sel:WORD_1
	v_mul_f32_e32 v37, 0xbfb8aa3b, v42
	v_exp_f32_e32 v37, v37
	s_nop 0
	v_add_f32_e32 v37, 1.0, v37
	v_rcp_f32_e32 v44, v37
	v_pk_mul_f32 v[32:33], v[36:37], v[32:33] op_sel_hi:[0,1]
	v_mul_f32_e32 v37, 0xbfb8aa3b, v43
	v_exp_f32_e32 v37, v37
	s_nop 0
	v_add_f32_e32 v37, 1.0, v37
	v_rcp_f32_e32 v45, v37
	v_pk_mul_f32 v[34:35], v[36:37], v[34:35] op_sel_hi:[0,1]
	v_pk_mul_f32 v[28:29], v[36:37], v[28:29] op_sel_hi:[0,1]
	v_pk_mul_f32 v[30:31], v[36:37], v[30:31] op_sel_hi:[0,1]
	v_pk_mul_f32 v[42:43], v[44:45], v[42:43]
	v_pk_mul_f32 v[24:25], v[36:37], v[24:25] op_sel_hi:[0,1]
	v_pk_mul_f32 v[32:33], v[32:33], v[42:43]
	v_pk_mul_f32 v[26:27], v[36:37], v[26:27] op_sel_hi:[0,1]
	v_cvt_pk_bf16_f32 v32, v32, v33
	v_mul_f32_e32 v33, 0xbfb8aa3b, v40
	v_exp_f32_e32 v33, v33
	v_pk_mul_f32 v[20:21], v[36:37], v[20:21] op_sel_hi:[0,1]
	v_pk_mul_f32 v[22:23], v[36:37], v[22:23] op_sel_hi:[0,1]
	v_add_f32_e32 v33, 1.0, v33
	v_rcp_f32_e32 v42, v33
	v_mul_f32_e32 v33, 0xbfb8aa3b, v41
	v_exp_f32_e32 v33, v33
	s_nop 0
	v_add_f32_e32 v33, 1.0, v33
	v_rcp_f32_e32 v43, v33
	s_nop 0
	v_pk_mul_f32 v[40:41], v[42:43], v[40:41]
	s_nop 0
	v_pk_mul_f32 v[34:35], v[34:35], v[40:41]
	s_nop 0
	v_cvt_pk_bf16_f32 v33, v34, v35
	v_lshl_add_u64 v[34:35], v[0:1], 0, v[38:39]
	global_store_dwordx2 v[34:35], v[32:33], off
	v_or_b32_e32 v32, 0xa0, v48
	v_mov_b32_e32 v33, v3
	v_lshl_add_u64 v[34:35], v[88:89], 0, v[32:33]
	v_mov_b32_e32 v34, v202
	v_mov_b32_e32 v35, v203
	v_cvt_f32_f16_e32 v38, v34
	v_cvt_f32_f16_sdwa v39, v34 dst_sel:DWORD dst_unused:UNUSED_PAD src0_sel:WORD_1
	v_mul_f32_e32 v34, 0xbfb8aa3b, v38
	v_exp_f32_e32 v34, v34
	s_nop 0
	v_add_f32_e32 v34, 1.0, v34
	v_rcp_f32_e32 v40, v34
	v_mul_f32_e32 v34, 0xbfb8aa3b, v39
	v_exp_f32_e32 v34, v34
	s_nop 0
	v_add_f32_e32 v34, 1.0, v34
	v_rcp_f32_e32 v41, v34
	v_cvt_f32_f16_e32 v34, v35
	v_cvt_f32_f16_sdwa v35, v35 dst_sel:DWORD dst_unused:UNUSED_PAD src0_sel:WORD_1
	v_pk_mul_f32 v[38:39], v[40:41], v[38:39]
	s_nop 0
	v_pk_mul_f32 v[28:29], v[28:29], v[38:39]
	s_nop 0
	v_cvt_pk_bf16_f32 v28, v28, v29
	v_mul_f32_e32 v29, 0xbfb8aa3b, v34
	v_exp_f32_e32 v29, v29
	s_nop 0
	v_add_f32_e32 v29, 1.0, v29
	v_rcp_f32_e32 v38, v29
	v_mul_f32_e32 v29, 0xbfb8aa3b, v35
	v_exp_f32_e32 v29, v29
	s_nop 0
	v_add_f32_e32 v29, 1.0, v29
	v_rcp_f32_e32 v39, v29
	s_nop 0
	v_pk_mul_f32 v[34:35], v[38:39], v[34:35]
	s_nop 0
	v_pk_mul_f32 v[30:31], v[30:31], v[34:35]
	s_nop 0
	v_cvt_pk_bf16_f32 v29, v30, v31
	v_lshl_add_u64 v[30:31], v[0:1], 0, v[32:33]
	global_store_dwordx2 v[30:31], v[28:29], off
	v_or_b32_e32 v28, 0xc0, v48
	v_mov_b32_e32 v29, v3
	v_lshl_add_u64 v[30:31], v[88:89], 0, v[28:29]
	v_mov_b32_e32 v30, v204
	v_mov_b32_e32 v31, v205
	v_cvt_f32_f16_e32 v32, v30
	v_cvt_f32_f16_sdwa v33, v30 dst_sel:DWORD dst_unused:UNUSED_PAD src0_sel:WORD_1
	v_mul_f32_e32 v30, 0xbfb8aa3b, v32
	v_exp_f32_e32 v30, v30
	s_nop 0
	v_add_f32_e32 v30, 1.0, v30
	v_rcp_f32_e32 v34, v30
	v_mul_f32_e32 v30, 0xbfb8aa3b, v33
	v_exp_f32_e32 v30, v30
	s_nop 0
	v_add_f32_e32 v30, 1.0, v30
	v_rcp_f32_e32 v35, v30
	v_cvt_f32_f16_e32 v30, v31
	v_cvt_f32_f16_sdwa v31, v31 dst_sel:DWORD dst_unused:UNUSED_PAD src0_sel:WORD_1
	v_pk_mul_f32 v[32:33], v[34:35], v[32:33]
	s_nop 0
	v_pk_mul_f32 v[24:25], v[24:25], v[32:33]
	s_nop 0
	v_cvt_pk_bf16_f32 v24, v24, v25
	v_mul_f32_e32 v25, 0xbfb8aa3b, v30
	v_exp_f32_e32 v25, v25
	s_nop 0
	v_add_f32_e32 v25, 1.0, v25
	v_rcp_f32_e32 v32, v25
	v_mul_f32_e32 v25, 0xbfb8aa3b, v31
	v_exp_f32_e32 v25, v25
	s_nop 0
	v_add_f32_e32 v25, 1.0, v25
	v_rcp_f32_e32 v33, v25
	s_nop 0
	v_pk_mul_f32 v[30:31], v[32:33], v[30:31]
	s_nop 0
	v_pk_mul_f32 v[26:27], v[26:27], v[30:31]
	s_nop 0
	v_cvt_pk_bf16_f32 v25, v26, v27
	v_lshl_add_u64 v[26:27], v[0:1], 0, v[28:29]
	global_store_dwordx2 v[26:27], v[24:25], off
	v_or_b32_e32 v24, 0xe0, v48
	v_mov_b32_e32 v25, v3
	v_lshl_add_u64 v[26:27], v[88:89], 0, v[24:25]
	v_mov_b32_e32 v26, v206
	v_mov_b32_e32 v27, v207
	v_cvt_f32_f16_e32 v28, v26
	v_cvt_f32_f16_sdwa v29, v26 dst_sel:DWORD dst_unused:UNUSED_PAD src0_sel:WORD_1
	v_mul_f32_e32 v26, 0xbfb8aa3b, v28
	v_exp_f32_e32 v26, v26
	s_nop 0
	v_add_f32_e32 v26, 1.0, v26
	v_rcp_f32_e32 v30, v26
	v_mul_f32_e32 v26, 0xbfb8aa3b, v29
	v_exp_f32_e32 v26, v26
	s_nop 0
	v_add_f32_e32 v26, 1.0, v26
	v_rcp_f32_e32 v31, v26
	v_cvt_f32_f16_e32 v26, v27
	v_cvt_f32_f16_sdwa v27, v27 dst_sel:DWORD dst_unused:UNUSED_PAD src0_sel:WORD_1
	v_pk_mul_f32 v[28:29], v[30:31], v[28:29]
	s_nop 0
	v_pk_mul_f32 v[20:21], v[20:21], v[28:29]
	s_nop 0
	v_cvt_pk_bf16_f32 v20, v20, v21
	v_mul_f32_e32 v21, 0xbfb8aa3b, v26
	v_exp_f32_e32 v21, v21
	s_nop 0
	v_add_f32_e32 v21, 1.0, v21
	v_rcp_f32_e32 v28, v21
	v_mul_f32_e32 v21, 0xbfb8aa3b, v27
	v_exp_f32_e32 v21, v21
	s_nop 0
	v_add_f32_e32 v21, 1.0, v21
	v_rcp_f32_e32 v29, v21
	s_nop 0
	v_pk_mul_f32 v[26:27], v[28:29], v[26:27]
	s_nop 0
	v_pk_mul_f32 v[22:23], v[22:23], v[26:27]
	s_nop 0
	v_cvt_pk_bf16_f32 v21, v22, v23
	v_lshl_add_u64 v[22:23], v[0:1], 0, v[24:25]
	global_store_dwordx2 v[22:23], v[20:21], off
	ds_read_b128 v[20:23], v133
	ds_read_b128 v[24:27], v133 offset:64
	s_waitcnt lgkmcnt(1)
; #define LAS __attribute__((address_space(3)))
; __device__ __forceinline__ float shx(float v, int lane, int m) { return __builtin_bit_cast(float, __builtin_amdgcn_ds_bpermute((lane ^ m) << 2, __builtin_bit_cast(int, v))); }
; __device__ __forceinline__ float ex2(float x) { return __builtin_amdgcn_exp2f(x); }
; template <bool FIRST>
; __device__ __forceinline__ void swa_item(const Params& p, int l, LAS unsigned char* lds, int item, int tid, int wave, int lane) {
;     ...
;         for (int t = 0; t < 9; ++t) { s[t] = (f32x4){0.f, 0.f, 0.f, 0.f};
; #pragma unroll
;             for (int ks = 0; ks < 2; ++ks) { const h8 a = *(const LAS h8*)(Ks + ((wave + t) * 16 + r) * SSTR + ks * 32 + g * 8);
;                 s[t] = __builtin_amdgcn_mfma_f32_16x16x32_f16(a, qf[ks], s[t], 0, 0, 0); } }
;         const float SC2 = 0.125f * 1.44269504f;
;         const float sink2 = p.sinks[l * 32 + hq] * 1.44269504f;
;         const int rg4 = r - 4 * g;
; #pragma unroll
;         for (int e = 0; e < 4; ++e) { s[0][e] = (rg4 < e) ? s[0][e] : -INFINITY; s[8][e] = (rg4 >= e) ? s[8][e] : -INFINITY; }
;         if (FIRST) {
; #pragma unroll
;             for (int t = 0; t < 9; ++t) { const bool tile_ok = (wave + t >= 8);
; #pragma unroll
;                 for (int e = 0; e < 4; ++e) s[t][e] = tile_ok ? s[t][e] : -INFINITY; }
;         }
;         float mr = -INFINITY;
; #pragma unroll
;         for (int t = 0; t < 9; ++t)
; #pragma unroll
;             for (int e = 0; e < 4; ++e) mr = fmaxf(mr, s[t][e]);
;         mr = fmaxf(mr, shx(mr, lane, 16)); mr = fmaxf(mr, shx(mr, lane, 32));
;         const float m = fmaxf(mr * SC2, sink2);
;         float ls = 0.f;
; #pragma unroll
;         for (int t = 0; t < 9; ++t)
; #pragma unroll
;             for (int e = 0; e < 4; ++e) { const float pv = ex2(__builtin_fmaf(s[t][e], SC2, -m)); s[t][e] = pv; ls += pv; }
;         ls += shx(ls, lane, 16); ls += shx(ls, lane, 32);
	v_mfma_f32_16x16x32_f16 v[20:23], v[20:23], v[16:19], 0
	ds_read_b128 v[54:57], v129 offset:64
	s_waitcnt lgkmcnt(1)
	v_mfma_f32_16x16x32_f16 v[50:53], v[24:27], v[12:15], v[20:23]
	ds_read_b128 v[24:27], v131 offset:64
	s_nop 3
	ds_read_b128 v[20:23], v131
	s_waitcnt lgkmcnt(0)
	v_mfma_f32_16x16x32_f16 v[20:23], v[20:23], v[16:19], 0
	v_cndmask_b32_e64 v49, v187, v53, s[54:55]
	v_mfma_f32_16x16x32_f16 v[44:47], v[24:27], v[12:15], v[20:23]
	ds_read_b128 v[24:27], v132 offset:64
	s_nop 4
	ds_read_b128 v[20:23], v132
	s_waitcnt lgkmcnt(0)
	v_mfma_f32_16x16x32_f16 v[20:23], v[20:23], v[16:19], 0
	v_mfma_f32_16x16x32_f16 v[40:43], v[24:27], v[12:15], v[20:23]
	ds_read_b128 v[24:27], v85 offset:64
	s_nop 5
	ds_read_b128 v[20:23], v85
	s_waitcnt lgkmcnt(0)
	v_mfma_f32_16x16x32_f16 v[20:23], v[20:23], v[16:19], 0
	v_mfma_f32_16x16x32_f16 v[36:39], v[24:27], v[12:15], v[20:23]
	ds_read_b128 v[24:27], v87 offset:64
	s_nop 5
	ds_read_b128 v[20:23], v87
	s_waitcnt lgkmcnt(0)
	v_mfma_f32_16x16x32_f16 v[20:23], v[20:23], v[16:19], 0
	v_mfma_f32_16x16x32_f16 v[32:35], v[24:27], v[12:15], v[20:23]
	ds_read_b128 v[24:27], v127 offset:64
	s_nop 5
	ds_read_b128 v[20:23], v127
	s_waitcnt lgkmcnt(0)
	v_mfma_f32_16x16x32_f16 v[20:23], v[20:23], v[16:19], 0
	v_mfma_f32_16x16x32_f16 v[28:31], v[24:27], v[12:15], v[20:23]
	ds_read_b128 v[24:27], v128 offset:64
	s_nop 5
	ds_read_b128 v[20:23], v128
	s_waitcnt lgkmcnt(0)
	v_mfma_f32_16x16x32_f16 v[20:23], v[20:23], v[16:19], 0
	v_mfma_f32_16x16x32_f16 v[24:27], v[24:27], v[12:15], v[20:23]
	s_nop 6
	ds_read_b128 v[20:23], v129
	s_waitcnt lgkmcnt(0)
	v_mfma_f32_16x16x32_f16 v[20:23], v[20:23], v[16:19], 0
	v_mfma_f32_16x16x32_f16 v[20:23], v[54:57], v[12:15], v[20:23]
	ds_read_b128 v[54:57], v130
	s_waitcnt lgkmcnt(0)
	v_mfma_f32_16x16x32_f16 v[16:19], v[54:57], v[16:19], 0
	ds_read_b128 v[54:57], v130 offset:64
	s_waitcnt lgkmcnt(0)
	v_mfma_f32_16x16x32_f16 v[12:15], v[54:57], v[12:15], v[16:19]
	s_nop 4
	v_mov_b32_e32 v16, v172
	v_cndmask_b32_e64 v17, v187, v50, s[48:49]
	v_cndmask_b32_e64 v18, v187, v51, s[50:51]
	v_cndmask_b32_e64 v19, v187, v52, s[52:53]
	v_max3_f32 v50, v17, s5, v18
	v_max3_f32 v50, v50, v19, v49
	v_max3_f32 v50, v50, v44, v45
	v_max3_f32 v50, v50, v46, v47
	v_max3_f32 v50, v50, v40, v41
	v_max3_f32 v50, v50, v42, v43
	v_max3_f32 v50, v50, v36, v37
	v_max3_f32 v50, v50, v38, v39
	v_max3_f32 v50, v50, v32, v33
	v_max3_f32 v50, v50, v34, v35
	v_max3_f32 v50, v50, v28, v29
	v_max3_f32 v50, v50, v30, v31
	v_max3_f32 v50, v50, v24, v25
	v_max3_f32 v50, v50, v26, v27
	v_max3_f32 v50, v50, v20, v21
	v_cndmask_b32_e64 v12, v12, v187, s[48:49]
	v_cndmask_b32_e64 v13, v13, v187, s[50:51]
	v_max3_f32 v50, v50, v22, v23
	v_cndmask_b32_e64 v14, v14, v187, s[52:53]
	v_cndmask_b32_e64 v15, v15, v187, s[54:55]
	v_max3_f32 v50, v50, v12, v13
	v_max3_f32 v50, v50, v14, v15
	ds_bpermute_b32 v52, v104, v50
	s_waitcnt lgkmcnt(0)
	v_max_f32_e32 v52, v52, v52
	v_max_f32_e32 v50, v50, v52
	ds_bpermute_b32 v52, v105, v50
	s_waitcnt lgkmcnt(0)
	v_max_f32_e32 v52, v52, v52
	v_max_f32_e32 v50, v50, v52
	v_mul_f32_e32 v50, 0x3e38aa3b, v50
	s_nop 0
	v_mul_f32_e32 v51, 0x3fb8aa3b, v16
	v_max_f32_e32 v50, v50, v51
	v_fma_f32 v17, v17, s44, -v50
	v_exp_f32_e32 v17, v17
	v_fma_f32 v18, v18, s44, -v50
	v_exp_f32_e32 v18, v18
	v_fma_f32 v19, v19, s44, -v50
	v_exp_f32_e32 v19, v19
	v_fma_f32 v49, v49, s44, -v50
	v_exp_f32_e32 v49, v49
	v_fma_f32 v44, v44, s44, -v50
	v_add_f32_e32 v51, 0, v17
	v_exp_f32_e32 v44, v44
	v_fma_f32 v45, v45, s44, -v50
	v_add_f32_e32 v51, v18, v51
	v_exp_f32_e32 v45, v45
	v_fma_f32 v46, v46, s44, -v50
	v_add_f32_e32 v51, v19, v51
	v_exp_f32_e32 v46, v46
	v_fma_f32 v47, v47, s44, -v50
	v_add_f32_e32 v51, v49, v51
	v_exp_f32_e32 v47, v47
	v_fma_f32 v40, v40, s44, -v50
	v_add_f32_e32 v51, v44, v51
	v_exp_f32_e32 v40, v40
	v_fma_f32 v41, v41, s44, -v50
	v_add_f32_e32 v51, v45, v51
	v_exp_f32_e32 v41, v41
	v_fma_f32 v42, v42, s44, -v50
	v_add_f32_e32 v51, v46, v51
	v_exp_f32_e32 v42, v42
	v_fma_f32 v43, v43, s44, -v50
	v_add_f32_e32 v51, v47, v51
	v_exp_f32_e32 v43, v43
	v_fma_f32 v36, v36, s44, -v50
	v_add_f32_e32 v51, v40, v51
	v_exp_f32_e32 v36, v36
	v_fma_f32 v37, v37, s44, -v50
	v_add_f32_e32 v51, v41, v51
	v_exp_f32_e32 v37, v37
	v_fma_f32 v38, v38, s44, -v50
	v_add_f32_e32 v51, v42, v51
	v_exp_f32_e32 v38, v38
	v_fma_f32 v39, v39, s44, -v50
	v_add_f32_e32 v51, v43, v51
	v_exp_f32_e32 v39, v39
	v_fma_f32 v32, v32, s44, -v50
	v_add_f32_e32 v51, v36, v51
	v_exp_f32_e32 v52, v32
	v_add_f32_e32 v51, v37, v51
	v_add_f32_e32 v51, v38, v51
	v_add_f32_e32 v51, v39, v51
	v_fma_f32 v33, v33, s44, -v50
	v_add_f32_e32 v32, v52, v51
	v_exp_f32_e32 v51, v33
	v_fma_f32 v33, v34, s44, -v50
	v_exp_f32_e32 v53, v33
	v_fma_f32 v33, v35, s44, -v50
	v_exp_f32_e32 v54, v33
	v_fma_f32 v28, v28, s44, -v50
	v_exp_f32_e32 v55, v28
	v_fma_f32 v29, v29, s44, -v50
	v_add_f32_e32 v32, v51, v32
	v_exp_f32_e32 v56, v29
	v_fma_f32 v29, v30, s44, -v50
	v_add_f32_e32 v32, v53, v32
	v_exp_f32_e32 v57, v29
	v_fma_f32 v29, v31, s44, -v50
	v_add_f32_e32 v32, v54, v32
	v_exp_f32_e32 v58, v29
	v_fma_f32 v24, v24, s44, -v50
	v_add_f32_e32 v28, v55, v32
	v_exp_f32_e32 v59, v24
	v_fma_f32 v25, v25, s44, -v50
	v_add_f32_e32 v28, v56, v28
	v_exp_f32_e32 v60, v25
	v_fma_f32 v25, v26, s44, -v50
	v_add_f32_e32 v28, v57, v28
	v_exp_f32_e32 v61, v25
	v_fma_f32 v25, v27, s44, -v50
	v_add_f32_e32 v28, v58, v28
	v_exp_f32_e32 v62, v25
	v_fma_f32 v20, v20, s44, -v50
	v_add_f32_e32 v24, v59, v28
	v_exp_f32_e32 v63, v20
	v_fma_f32 v21, v21, s44, -v50
	v_add_f32_e32 v24, v60, v24
	v_exp_f32_e32 v64, v21
	v_fma_f32 v21, v22, s44, -v50
	v_add_f32_e32 v24, v61, v24
	v_exp_f32_e32 v65, v21
	v_fma_f32 v21, v23, s44, -v50
	v_add_f32_e32 v24, v62, v24
	v_exp_f32_e32 v66, v21
	v_fma_f32 v12, v12, s44, -v50
	v_add_f32_e32 v20, v63, v24
	v_exp_f32_e32 v67, v12
	v_fma_f32 v13, v13, s44, -v50
	v_add_f32_e32 v20, v64, v20
	v_exp_f32_e32 v134, v13
	v_fma_f32 v13, v14, s44, -v50
	v_add_f32_e32 v20, v65, v20
	v_exp_f32_e32 v135, v13
	v_fma_f32 v13, v15, s44, -v50
	v_add_f32_e32 v20, v66, v20
	v_exp_f32_e32 v136, v13
	v_add_f32_e32 v12, v67, v20
	v_add_f32_e32 v12, v134, v12
	v_add_f32_e32 v12, v135, v12
	v_add_f32_e32 v12, v136, v12
	ds_bpermute_b32 v13, v104, v12
	v_cvt_pk_f16_f32 v15, v46, v47
	v_cvt_pk_f16_f32 v14, v44, v45
	s_waitcnt lgkmcnt(0)
; #define LAS __attribute__((address_space(3)))
; __device__ __forceinline__ float shx(float v, int lane, int m) { return __builtin_bit_cast(float, __builtin_amdgcn_ds_bpermute((lane ^ m) << 2, __builtin_bit_cast(int, v))); }
; __device__ __forceinline__ float ex2(float x) { return __builtin_amdgcn_exp2f(x); }
; __device__ __forceinline__ h4 tr_read(const LAS half_t* p) { s4v r = __builtin_amdgcn_ds_read_tr16_b64_v4i16((LAS s4v*)p); return __builtin_bit_cast(h4, r); }
; template <bool FIRST>
; __device__ __forceinline__ void swa_item(const Params& p, int l, LAS unsigned char* lds, int item, int tid, int wave, int lane) {
;     ...
;         ls += shx(ls, lane, 16); ls += shx(ls, lane, 32);
;         ls += ex2(sink2 - m);
;         const float inv = __builtin_amdgcn_rcpf(ls);
;         f32x4 o[4];
; #pragma unroll
;         for (int i = 0; i < 4; ++i) o[i] = (f32x4){0.f, 0.f, 0.f, 0.f};
; #pragma unroll
;         for (int pr = 0; pr < 5; ++pr) {
;             h8 bp;
; #pragma unroll
;             for (int e = 0; e < 4; ++e) { bp[e] = (half_t)s[2 * pr][e]; bp[4 + e] = (pr < 4) ? (half_t)s[(pr < 4) ? 2 * pr + 1 : 0][e] : (half_t)0.f; }
; #pragma unroll
;             for (int mt = 0; mt < 4; ++mt) { const LAS half_t* vp = Vs + ((wave + 2 * pr) * 16 + 4 * g + q) * SSTR + mt * 16 + 4 * pp;
;                 const h8 af = cat8(tr_read(vp), tr_read(vp + 16 * SSTR));
;                 o[mt] = __builtin_amdgcn_mfma_f32_16x16x32_f16(af, bp, o[mt], 0, 0, 0); }
;         }
	v_add_f32_e32 v12, v12, v13
	ds_bpermute_b32 v13, v105, v12
	s_waitcnt lgkmcnt(0)
	v_add_f32_e32 v12, v12, v13
	v_fma_f32 v13, v16, s11, -v50
	v_exp_f32_e32 v13, v13
	s_nop 0
	v_add_f32_e32 v50, v13, v12
	v_cvt_pk_f16_f32 v13, v19, v49
	v_cvt_pk_f16_f32 v12, v17, v18
	ds_read_b64_tr_b16 v[18:19], v115 offset:41472
	ds_read_b64_tr_b16 v[16:17], v115 offset:39168
	ds_read_b64_tr_b16 v[20:21], v115 offset:39200
	ds_read_b64_tr_b16 v[22:23], v115 offset:41504
	ds_read_b64_tr_b16 v[24:25], v115 offset:39232
	ds_read_b64_tr_b16 v[26:27], v115 offset:41536
	ds_read_b64_tr_b16 v[28:29], v115 offset:39264
	ds_read_b64_tr_b16 v[30:31], v115 offset:41568
	ds_read_b64_tr_b16 v[32:33], v115 offset:43776
	ds_read_b64_tr_b16 v[34:35], v115 offset:46080
	s_waitcnt lgkmcnt(8)
	v_mfma_f32_16x16x32_f16 v[16:19], v[16:19], v[12:15], 0
	s_waitcnt lgkmcnt(6)
	v_mfma_f32_16x16x32_f16 v[20:23], v[20:23], v[12:15], 0
	s_waitcnt lgkmcnt(4)
	v_mfma_f32_16x16x32_f16 v[24:27], v[24:27], v[12:15], 0
	s_waitcnt lgkmcnt(2)
	v_mfma_f32_16x16x32_f16 v[12:15], v[28:31], v[12:15], 0
	v_cvt_pk_f16_f32 v31, v38, v39
	v_cvt_pk_f16_f32 v30, v36, v37
	v_cvt_pk_f16_f32 v29, v42, v43
	v_cvt_pk_f16_f32 v28, v40, v41
	s_waitcnt lgkmcnt(0)
	s_nop 0
	v_mfma_f32_16x16x32_f16 v[16:19], v[32:35], v[28:31], v[16:19]
	ds_read_b64_tr_b16 v[32:33], v115 offset:43808
	ds_read_b64_tr_b16 v[34:35], v115 offset:46112
	s_waitcnt lgkmcnt(0)
	v_mfma_f32_16x16x32_f16 v[20:23], v[32:35], v[28:31], v[20:23]
	ds_read_b64_tr_b16 v[32:33], v115 offset:43840
	ds_read_b64_tr_b16 v[34:35], v115 offset:46144
	s_waitcnt lgkmcnt(0)
	v_mfma_f32_16x16x32_f16 v[24:27], v[32:35], v[28:31], v[24:27]
	ds_read_b64_tr_b16 v[32:33], v115 offset:43872
	ds_read_b64_tr_b16 v[34:35], v115 offset:46176
	s_waitcnt lgkmcnt(0)
	v_mfma_f32_16x16x32_f16 v[12:15], v[32:35], v[28:31], v[12:15]
	ds_read_b64_tr_b16 v[32:33], v115 offset:48384
	ds_read_b64_tr_b16 v[34:35], v115 offset:50688
	v_cvt_pk_f16_f32 v31, v57, v58
	v_cvt_pk_f16_f32 v30, v55, v56
	v_cvt_pk_f16_f32 v29, v53, v54
	v_cvt_pk_f16_f32 v28, v52, v51
	s_waitcnt lgkmcnt(0)
	s_nop 0
	v_mfma_f32_16x16x32_f16 v[16:19], v[32:35], v[28:31], v[16:19]
	ds_read_b64_tr_b16 v[32:33], v115 offset:48416
	ds_read_b64_tr_b16 v[34:35], v115 offset:50720
	s_waitcnt lgkmcnt(0)
	v_mfma_f32_16x16x32_f16 v[20:23], v[32:35], v[28:31], v[20:23]
	ds_read_b64_tr_b16 v[32:33], v115 offset:48448
	ds_read_b64_tr_b16 v[34:35], v115 offset:50752
	s_waitcnt lgkmcnt(0)
	v_mfma_f32_16x16x32_f16 v[24:27], v[32:35], v[28:31], v[24:27]
	ds_read_b64_tr_b16 v[32:33], v115 offset:48480
	ds_read_b64_tr_b16 v[34:35], v115 offset:50784
	s_waitcnt lgkmcnt(0)
	v_mfma_f32_16x16x32_f16 v[12:15], v[32:35], v[28:31], v[12:15]
	ds_read_b64_tr_b16 v[32:33], v115 offset:52992
	ds_read_b64_tr_b16 v[34:35], v115 offset:55296
	v_cvt_pk_f16_f32 v31, v65, v66
	v_cvt_pk_f16_f32 v30, v63, v64
	v_cvt_pk_f16_f32 v29, v61, v62
	v_cvt_pk_f16_f32 v28, v59, v60
	s_waitcnt lgkmcnt(0)
	s_nop 0
	v_mfma_f32_16x16x32_f16 v[16:19], v[32:35], v[28:31], v[16:19]
	ds_read_b64_tr_b16 v[32:33], v115 offset:53024
	ds_read_b64_tr_b16 v[34:35], v115 offset:55328
	s_waitcnt lgkmcnt(0)
	v_mfma_f32_16x16x32_f16 v[20:23], v[32:35], v[28:31], v[20:23]
	ds_read_b64_tr_b16 v[32:33], v115 offset:53056
	ds_read_b64_tr_b16 v[34:35], v115 offset:55360
	s_waitcnt lgkmcnt(0)
	v_mfma_f32_16x16x32_f16 v[32:35], v[32:35], v[28:31], v[24:27]
	s_nop 2
	ds_read_b64_tr_b16 v[24:25], v115 offset:53088
	ds_read_b64_tr_b16 v[26:27], v115 offset:55392
	s_waitcnt lgkmcnt(0)
	v_mfma_f32_16x16x32_f16 v[12:15], v[24:27], v[28:31], v[12:15]
	ds_read_b64_tr_b16 v[24:25], v115 offset:57600
	ds_read_b64_tr_b16 v[26:27], v115 offset:59904
	v_cvt_pk_f16_f32 v29, v135, v136
	v_cvt_pk_f16_f32 v28, v67, v134
	v_mov_b32_e32 v30, v3
	v_mov_b32_e32 v31, v3
	s_waitcnt lgkmcnt(0)
	s_nop 0
	v_mfma_f32_16x16x32_f16 v[24:27], v[24:27], v[28:31], v[16:19]
	s_nop 2
	ds_read_b64_tr_b16 v[16:17], v115 offset:57632
	ds_read_b64_tr_b16 v[18:19], v115 offset:59936
	s_waitcnt lgkmcnt(0)
	v_mfma_f32_16x16x32_f16 v[20:23], v[16:19], v[28:31], v[20:23]
	ds_read_b64_tr_b16 v[16:17], v115 offset:57664
	ds_read_b64_tr_b16 v[18:19], v115 offset:59968
	s_waitcnt lgkmcnt(0)
	v_mfma_f32_16x16x32_f16 v[16:19], v[16:19], v[28:31], v[32:35]
	s_nop 2
	ds_read_b64_tr_b16 v[32:33], v115 offset:57696
	ds_read_b64_tr_b16 v[34:35], v115 offset:60000
	s_waitcnt lgkmcnt(0)
; #define LAS __attribute__((address_space(3)))
; __device__ __forceinline__ float siluf(float x) { return x * __builtin_amdgcn_rcpf(1.f + ex2(x * -1.44269504f)); }
; template <bool FIRST>
; __device__ __forceinline__ void swa_item(const Params& p, int l, LAS unsigned char* lds, int item, int tid, int wave, int lane) {
;     ...
;         for (int t = 0; t < 9; ++t) { s[t] = (f32x4){0.f, 0.f, 0.f, 0.f};
; #pragma unroll
;             for (int ks = 0; ks < 2; ++ks) { const h8 a = *(const LAS h8*)(Ks + ((wave + t) * 16 + r) * SSTR + ks * 32 + g * 8);
;                 s[t] = __builtin_amdgcn_mfma_f32_16x16x32_f16(a, qf[ks], s[t], 0, 0, 0); } }
;     ...
; #pragma unroll
;         for (int mt = 0; mt < 4; ++mt) { const int col = hq * 64 + mt * 16 + 4 * g;
;             const h4 sg = *(const h4*)(PR + (size_t)tok * NIN + C_SG + col);
;             h4 y;
; #pragma unroll
;             for (int e = 0; e < 4; ++e) y[e] = op16(o[mt][e] * inv * siluf((float)sg[e]), TAIL_BF16);
;             *(h4*)(RA + (size_t)tok * 4096 + 2048 + col) = y; }
	v_mfma_f32_16x16x32_f16 v[12:15], v[32:35], v[28:31], v[12:15]
	v_or_b32_e32 v30, 0x100, v48
	v_lshl_add_u64 v[32:33], v[88:89], 0, v[30:31]
	v_mov_b32_e32 v32, v208
	v_rcp_f32_e32 v28, v50
	v_mov_b32_e32 v33, v209
	v_cvt_f32_f16_e32 v34, v32
	v_cvt_f32_f16_sdwa v35, v32 dst_sel:DWORD dst_unused:UNUSED_PAD src0_sel:WORD_1
	v_cvt_f32_f16_e32 v32, v33
	v_cvt_f32_f16_sdwa v33, v33 dst_sel:DWORD dst_unused:UNUSED_PAD src0_sel:WORD_1
	v_mul_f32_e32 v29, 0xbfb8aa3b, v34
	v_exp_f32_e32 v29, v29
	s_nop 0
	v_add_f32_e32 v29, 1.0, v29
	v_rcp_f32_e32 v36, v29
	v_pk_mul_f32 v[24:25], v[28:29], v[24:25] op_sel_hi:[0,1]
	v_mul_f32_e32 v29, 0xbfb8aa3b, v35
	v_exp_f32_e32 v29, v29
	s_nop 0
	v_add_f32_e32 v29, 1.0, v29
	v_rcp_f32_e32 v37, v29
	v_pk_mul_f32 v[26:27], v[28:29], v[26:27] op_sel_hi:[0,1]
	v_pk_mul_f32 v[20:21], v[28:29], v[20:21] op_sel_hi:[0,1]
	v_pk_mul_f32 v[22:23], v[28:29], v[22:23] op_sel_hi:[0,1]
	v_pk_mul_f32 v[34:35], v[36:37], v[34:35]
	v_pk_mul_f32 v[16:17], v[28:29], v[16:17] op_sel_hi:[0,1]
	v_pk_mul_f32 v[24:25], v[24:25], v[34:35]
	v_pk_mul_f32 v[18:19], v[28:29], v[18:19] op_sel_hi:[0,1]
	v_cvt_pk_bf16_f32 v24, v24, v25
	v_mul_f32_e32 v25, 0xbfb8aa3b, v32
	v_exp_f32_e32 v25, v25
	v_pk_mul_f32 v[12:13], v[28:29], v[12:13] op_sel_hi:[0,1]
	v_pk_mul_f32 v[14:15], v[28:29], v[14:15] op_sel_hi:[0,1]
	v_add_f32_e32 v25, 1.0, v25
	v_rcp_f32_e32 v34, v25
	v_mul_f32_e32 v25, 0xbfb8aa3b, v33
	v_exp_f32_e32 v25, v25
	s_nop 0
	v_add_f32_e32 v25, 1.0, v25
	v_rcp_f32_e32 v35, v25
	s_nop 0
	v_pk_mul_f32 v[32:33], v[34:35], v[32:33]
	s_nop 0
	v_pk_mul_f32 v[26:27], v[26:27], v[32:33]
	s_nop 0
	v_cvt_pk_bf16_f32 v25, v26, v27
	v_lshl_add_u64 v[26:27], v[0:1], 0, v[30:31]
	global_store_dwordx2 v[26:27], v[24:25], off
	v_or_b32_e32 v24, 0x120, v48
	v_mov_b32_e32 v25, v3
	v_lshl_add_u64 v[26:27], v[88:89], 0, v[24:25]
	v_mov_b32_e32 v26, v210
	v_mov_b32_e32 v27, v211
	v_cvt_f32_f16_e32 v30, v26
	v_cvt_f32_f16_sdwa v31, v26 dst_sel:DWORD dst_unused:UNUSED_PAD src0_sel:WORD_1
	v_mul_f32_e32 v26, 0xbfb8aa3b, v30
	v_exp_f32_e32 v26, v26
	s_nop 0
	v_add_f32_e32 v26, 1.0, v26
	v_rcp_f32_e32 v32, v26
	v_mul_f32_e32 v26, 0xbfb8aa3b, v31
	v_exp_f32_e32 v26, v26
	s_nop 0
	v_add_f32_e32 v26, 1.0, v26
	v_rcp_f32_e32 v33, v26
	v_cvt_f32_f16_e32 v26, v27
	v_cvt_f32_f16_sdwa v27, v27 dst_sel:DWORD dst_unused:UNUSED_PAD src0_sel:WORD_1
	v_pk_mul_f32 v[30:31], v[32:33], v[30:31]
	s_nop 0
	v_pk_mul_f32 v[20:21], v[20:21], v[30:31]
	s_nop 0
	v_cvt_pk_bf16_f32 v20, v20, v21
	v_mul_f32_e32 v21, 0xbfb8aa3b, v26
	v_exp_f32_e32 v21, v21
	s_nop 0
	v_add_f32_e32 v21, 1.0, v21
	v_rcp_f32_e32 v30, v21
	v_mul_f32_e32 v21, 0xbfb8aa3b, v27
	v_exp_f32_e32 v21, v21
	s_nop 0
	v_add_f32_e32 v21, 1.0, v21
	v_rcp_f32_e32 v31, v21
	s_nop 0
	v_pk_mul_f32 v[26:27], v[30:31], v[26:27]
	s_nop 0
	v_pk_mul_f32 v[22:23], v[22:23], v[26:27]
	s_nop 0
	v_cvt_pk_bf16_f32 v21, v22, v23
	v_lshl_add_u64 v[22:23], v[0:1], 0, v[24:25]
	global_store_dwordx2 v[22:23], v[20:21], off
	v_or_b32_e32 v20, 0x140, v48
	v_mov_b32_e32 v21, v3
	v_lshl_add_u64 v[22:23], v[88:89], 0, v[20:21]
	v_mov_b32_e32 v22, v212
	v_mov_b32_e32 v23, v213
	v_cvt_f32_f16_e32 v24, v22
	v_cvt_f32_f16_sdwa v25, v22 dst_sel:DWORD dst_unused:UNUSED_PAD src0_sel:WORD_1
	v_mul_f32_e32 v22, 0xbfb8aa3b, v24
	v_exp_f32_e32 v22, v22
	s_nop 0
	v_add_f32_e32 v22, 1.0, v22
	v_rcp_f32_e32 v26, v22
	v_mul_f32_e32 v22, 0xbfb8aa3b, v25
	v_exp_f32_e32 v22, v22
	s_nop 0
	v_add_f32_e32 v22, 1.0, v22
	v_rcp_f32_e32 v27, v22
	v_cvt_f32_f16_e32 v22, v23
	v_cvt_f32_f16_sdwa v23, v23 dst_sel:DWORD dst_unused:UNUSED_PAD src0_sel:WORD_1
	v_pk_mul_f32 v[24:25], v[26:27], v[24:25]
	s_nop 0
	v_pk_mul_f32 v[16:17], v[16:17], v[24:25]
	s_nop 0
	v_cvt_pk_bf16_f32 v16, v16, v17
	v_mul_f32_e32 v17, 0xbfb8aa3b, v22
	v_exp_f32_e32 v17, v17
	s_nop 0
	v_add_f32_e32 v17, 1.0, v17
	v_rcp_f32_e32 v24, v17
	v_mul_f32_e32 v17, 0xbfb8aa3b, v23
	v_exp_f32_e32 v17, v17
	s_nop 0
	v_add_f32_e32 v17, 1.0, v17
	v_rcp_f32_e32 v25, v17
	s_nop 0
	v_pk_mul_f32 v[22:23], v[24:25], v[22:23]
	s_nop 0
	v_pk_mul_f32 v[18:19], v[18:19], v[22:23]
	s_nop 0
	v_cvt_pk_bf16_f32 v17, v18, v19
	v_lshl_add_u64 v[18:19], v[0:1], 0, v[20:21]
	global_store_dwordx2 v[18:19], v[16:17], off
	v_or_b32_e32 v16, 0x160, v48
	v_mov_b32_e32 v17, v3
	v_lshl_add_u64 v[18:19], v[88:89], 0, v[16:17]
	v_mov_b32_e32 v18, v214
	v_mov_b32_e32 v19, v215
	v_cvt_f32_f16_e32 v20, v18
	v_cvt_f32_f16_sdwa v21, v18 dst_sel:DWORD dst_unused:UNUSED_PAD src0_sel:WORD_1
	v_mul_f32_e32 v18, 0xbfb8aa3b, v20
	v_exp_f32_e32 v18, v18
	s_nop 0
	v_add_f32_e32 v18, 1.0, v18
	v_rcp_f32_e32 v22, v18
	v_mul_f32_e32 v18, 0xbfb8aa3b, v21
	v_exp_f32_e32 v18, v18
	s_nop 0
	v_add_f32_e32 v18, 1.0, v18
	v_rcp_f32_e32 v23, v18
	v_cvt_f32_f16_e32 v18, v19
	v_cvt_f32_f16_sdwa v19, v19 dst_sel:DWORD dst_unused:UNUSED_PAD src0_sel:WORD_1
	v_pk_mul_f32 v[20:21], v[22:23], v[20:21]
	s_nop 0
	v_pk_mul_f32 v[12:13], v[12:13], v[20:21]
	s_nop 0
	v_cvt_pk_bf16_f32 v12, v12, v13
	v_mul_f32_e32 v13, 0xbfb8aa3b, v18
	v_exp_f32_e32 v13, v13
	s_nop 0
	v_add_f32_e32 v13, 1.0, v13
	v_rcp_f32_e32 v20, v13
	v_mul_f32_e32 v13, 0xbfb8aa3b, v19
	v_exp_f32_e32 v13, v13
	s_nop 0
	v_add_f32_e32 v13, 1.0, v13
	v_rcp_f32_e32 v21, v13
	s_nop 0
	v_pk_mul_f32 v[18:19], v[20:21], v[18:19]
	s_nop 0
	v_pk_mul_f32 v[14:15], v[14:15], v[18:19]
	s_nop 0
	v_cvt_pk_bf16_f32 v13, v14, v15
	v_lshl_add_u64 v[14:15], v[0:1], 0, v[16:17]
	global_store_dwordx2 v[14:15], v[12:13], off
	ds_read_b128 v[12:15], v133
	ds_read_b128 v[16:19], v133 offset:64
	s_waitcnt lgkmcnt(1)
	v_mfma_f32_16x16x32_f16 v[12:15], v[12:15], v[4:7], 0
	ds_read_b128 v[44:47], v129 offset:64
	s_waitcnt lgkmcnt(1)
; #define LAS __attribute__((address_space(3)))
; __device__ __forceinline__ float shx(float v, int lane, int m) { return __builtin_bit_cast(float, __builtin_amdgcn_ds_bpermute((lane ^ m) << 2, __builtin_bit_cast(int, v))); }
; __device__ __forceinline__ float ex2(float x) { return __builtin_amdgcn_exp2f(x); }
; template <bool FIRST>
; __device__ __forceinline__ void swa_item(const Params& p, int l, LAS unsigned char* lds, int item, int tid, int wave, int lane) {
;     ...
;         for (int t = 0; t < 9; ++t) { s[t] = (f32x4){0.f, 0.f, 0.f, 0.f};
; #pragma unroll
;             for (int ks = 0; ks < 2; ++ks) { const h8 a = *(const LAS h8*)(Ks + ((wave + t) * 16 + r) * SSTR + ks * 32 + g * 8);
;                 s[t] = __builtin_amdgcn_mfma_f32_16x16x32_f16(a, qf[ks], s[t], 0, 0, 0); } }
;         const float SC2 = 0.125f * 1.44269504f;
;         const float sink2 = p.sinks[l * 32 + hq] * 1.44269504f;
;         const int rg4 = r - 4 * g;
; #pragma unroll
;         for (int e = 0; e < 4; ++e) { s[0][e] = (rg4 < e) ? s[0][e] : -INFINITY; s[8][e] = (rg4 >= e) ? s[8][e] : -INFINITY; }
;         if (FIRST) {
; #pragma unroll
;             for (int t = 0; t < 9; ++t) { const bool tile_ok = (wave + t >= 8);
; #pragma unroll
;                 for (int e = 0; e < 4; ++e) s[t][e] = tile_ok ? s[t][e] : -INFINITY; }
;         }
;         float mr = -INFINITY;
; #pragma unroll
;         for (int t = 0; t < 9; ++t)
; #pragma unroll
;             for (int e = 0; e < 4; ++e) mr = fmaxf(mr, s[t][e]);
;         mr = fmaxf(mr, shx(mr, lane, 16)); mr = fmaxf(mr, shx(mr, lane, 32));
;         const float m = fmaxf(mr * SC2, sink2);
;         float ls = 0.f;
; #pragma unroll
;         for (int t = 0; t < 9; ++t)
; #pragma unroll
;             for (int e = 0; e < 4; ++e) { const float pv = ex2(__builtin_fmaf(s[t][e], SC2, -m)); s[t][e] = pv; ls += pv; }
;         ls += shx(ls, lane, 16); ls += shx(ls, lane, 32);
	v_mfma_f32_16x16x32_f16 v[40:43], v[16:19], v[8:11], v[12:15]
	ds_read_b128 v[16:19], v131 offset:64
	s_nop 3
	ds_read_b128 v[12:15], v131
	s_waitcnt lgkmcnt(0)
	v_mfma_f32_16x16x32_f16 v[12:15], v[12:15], v[4:7], 0
	v_mfma_f32_16x16x32_f16 v[36:39], v[16:19], v[8:11], v[12:15]
	ds_read_b128 v[16:19], v132 offset:64
	s_nop 5
	ds_read_b128 v[12:15], v132
	s_waitcnt lgkmcnt(0)
	v_mfma_f32_16x16x32_f16 v[12:15], v[12:15], v[4:7], 0
	v_mfma_f32_16x16x32_f16 v[32:35], v[16:19], v[8:11], v[12:15]
	ds_read_b128 v[16:19], v85 offset:64
	s_nop 5
	ds_read_b128 v[12:15], v85
	s_waitcnt lgkmcnt(0)
	v_mfma_f32_16x16x32_f16 v[12:15], v[12:15], v[4:7], 0
	v_mfma_f32_16x16x32_f16 v[28:31], v[16:19], v[8:11], v[12:15]
	ds_read_b128 v[16:19], v87 offset:64
	s_nop 5
	ds_read_b128 v[12:15], v87
	s_waitcnt lgkmcnt(0)
	v_mfma_f32_16x16x32_f16 v[12:15], v[12:15], v[4:7], 0
	v_mfma_f32_16x16x32_f16 v[24:27], v[16:19], v[8:11], v[12:15]
	ds_read_b128 v[16:19], v127 offset:64
	s_nop 5
	ds_read_b128 v[12:15], v127
	s_waitcnt lgkmcnt(0)
	v_mfma_f32_16x16x32_f16 v[12:15], v[12:15], v[4:7], 0
	v_mfma_f32_16x16x32_f16 v[20:23], v[16:19], v[8:11], v[12:15]
	ds_read_b128 v[16:19], v128 offset:64
	s_nop 5
	ds_read_b128 v[12:15], v128
	s_waitcnt lgkmcnt(0)
	v_mfma_f32_16x16x32_f16 v[12:15], v[12:15], v[4:7], 0
	v_mfma_f32_16x16x32_f16 v[16:19], v[16:19], v[8:11], v[12:15]
	s_nop 6
	ds_read_b128 v[12:15], v129
	s_waitcnt lgkmcnt(0)
	v_mfma_f32_16x16x32_f16 v[12:15], v[12:15], v[4:7], 0
	v_mfma_f32_16x16x32_f16 v[12:15], v[44:47], v[8:11], v[12:15]
	ds_read_b128 v[44:47], v130
	s_waitcnt lgkmcnt(0)
	v_mfma_f32_16x16x32_f16 v[4:7], v[44:47], v[4:7], 0
	ds_read_b128 v[44:47], v130 offset:64
	s_waitcnt lgkmcnt(0)
	v_mfma_f32_16x16x32_f16 v[6:9], v[44:47], v[8:11], v[4:7]
	s_nop 4
	v_mov_b32_e32 v4, v173
	v_cndmask_b32_e64 v10, v187, v40, s[48:49]
	v_cndmask_b32_e64 v11, v187, v41, s[50:51]
	v_cndmask_b32_e64 v40, v187, v42, s[52:53]
	v_cndmask_b32_e64 v41, v187, v43, s[54:55]
	v_max3_f32 v5, v10, s5, v11
	v_max3_f32 v5, v5, v40, v41
	v_max3_f32 v5, v5, v36, v37
	v_max3_f32 v5, v5, v38, v39
	v_max3_f32 v5, v5, v32, v33
	v_max3_f32 v5, v5, v34, v35
	v_max3_f32 v5, v5, v28, v29
	v_max3_f32 v5, v5, v30, v31
	v_max3_f32 v5, v5, v24, v25
	v_max3_f32 v5, v5, v26, v27
	v_max3_f32 v5, v5, v20, v21
	v_max3_f32 v5, v5, v22, v23
	v_max3_f32 v5, v5, v16, v17
	v_max3_f32 v5, v5, v18, v19
	v_max3_f32 v5, v5, v12, v13
	v_cndmask_b32_e64 v6, v6, v187, s[48:49]
	v_cndmask_b32_e64 v7, v7, v187, s[50:51]
	v_max3_f32 v5, v5, v14, v15
	v_cndmask_b32_e64 v8, v8, v187, s[52:53]
	v_cndmask_b32_e64 v9, v9, v187, s[54:55]
	v_max3_f32 v5, v5, v6, v7
	v_max3_f32 v5, v5, v8, v9
	ds_bpermute_b32 v43, v104, v5
	s_waitcnt lgkmcnt(0)
	v_max_f32_e32 v43, v43, v43
	v_max_f32_e32 v5, v5, v43
	ds_bpermute_b32 v43, v105, v5
	s_waitcnt lgkmcnt(0)
	v_max_f32_e32 v43, v43, v43
	v_max_f32_e32 v5, v5, v43
	v_mul_f32_e32 v5, 0x3e38aa3b, v5
	s_nop 0
	v_mul_f32_e32 v42, 0x3fb8aa3b, v4
	v_max_f32_e32 v5, v5, v42
	v_fma_f32 v10, v10, s44, -v5
	v_exp_f32_e32 v10, v10
	v_fma_f32 v11, v11, s44, -v5
	v_exp_f32_e32 v11, v11
	v_fma_f32 v40, v40, s44, -v5
	v_exp_f32_e32 v40, v40
	v_fma_f32 v41, v41, s44, -v5
	v_exp_f32_e32 v41, v41
	v_fma_f32 v36, v36, s44, -v5
	v_add_f32_e32 v42, 0, v10
	v_exp_f32_e32 v36, v36
	v_fma_f32 v37, v37, s44, -v5
	v_add_f32_e32 v42, v11, v42
	v_exp_f32_e32 v37, v37
	v_fma_f32 v38, v38, s44, -v5
	v_add_f32_e32 v42, v40, v42
	v_exp_f32_e32 v38, v38
	v_fma_f32 v39, v39, s44, -v5
	v_add_f32_e32 v42, v41, v42
	v_exp_f32_e32 v39, v39
	v_fma_f32 v32, v32, s44, -v5
	v_add_f32_e32 v42, v36, v42
	v_exp_f32_e32 v32, v32
	v_fma_f32 v33, v33, s44, -v5
	v_add_f32_e32 v42, v37, v42
	v_exp_f32_e32 v33, v33
	v_fma_f32 v34, v34, s44, -v5
	v_add_f32_e32 v42, v38, v42
	v_exp_f32_e32 v34, v34
	v_fma_f32 v35, v35, s44, -v5
	v_add_f32_e32 v42, v39, v42
	v_exp_f32_e32 v35, v35
	v_fma_f32 v28, v28, s44, -v5
	v_add_f32_e32 v42, v32, v42
	v_exp_f32_e32 v28, v28
	v_fma_f32 v29, v29, s44, -v5
	v_add_f32_e32 v42, v33, v42
	v_exp_f32_e32 v29, v29
	v_fma_f32 v30, v30, s44, -v5
	v_add_f32_e32 v42, v34, v42
	v_exp_f32_e32 v30, v30
	v_fma_f32 v31, v31, s44, -v5
	v_add_f32_e32 v42, v35, v42
	v_exp_f32_e32 v31, v31
	v_fma_f32 v24, v24, s44, -v5
	v_add_f32_e32 v42, v28, v42
	v_exp_f32_e32 v43, v24
	v_add_f32_e32 v42, v29, v42
	v_add_f32_e32 v42, v30, v42
	v_add_f32_e32 v42, v31, v42
	v_fma_f32 v25, v25, s44, -v5
	v_add_f32_e32 v24, v43, v42
	v_exp_f32_e32 v42, v25
	v_fma_f32 v25, v26, s44, -v5
	v_exp_f32_e32 v44, v25
	v_fma_f32 v25, v27, s44, -v5
	v_exp_f32_e32 v45, v25
	v_fma_f32 v20, v20, s44, -v5
	v_exp_f32_e32 v46, v20
	v_fma_f32 v21, v21, s44, -v5
	v_add_f32_e32 v24, v42, v24
	v_exp_f32_e32 v47, v21
	v_fma_f32 v21, v22, s44, -v5
	v_add_f32_e32 v24, v44, v24
	v_exp_f32_e32 v49, v21
	v_fma_f32 v21, v23, s44, -v5
	v_add_f32_e32 v24, v45, v24
	v_exp_f32_e32 v50, v21
	v_fma_f32 v16, v16, s44, -v5
	v_add_f32_e32 v20, v46, v24
	v_exp_f32_e32 v51, v16
	v_fma_f32 v17, v17, s44, -v5
	v_add_f32_e32 v20, v47, v20
	v_exp_f32_e32 v52, v17
	v_fma_f32 v17, v18, s44, -v5
	v_add_f32_e32 v20, v49, v20
	v_exp_f32_e32 v53, v17
	v_fma_f32 v17, v19, s44, -v5
	v_add_f32_e32 v20, v50, v20
	v_exp_f32_e32 v54, v17
	v_fma_f32 v12, v12, s44, -v5
	v_add_f32_e32 v16, v51, v20
	v_exp_f32_e32 v55, v12
	v_fma_f32 v13, v13, s44, -v5
	v_add_f32_e32 v16, v52, v16
	v_exp_f32_e32 v56, v13
	v_fma_f32 v13, v14, s44, -v5
	v_add_f32_e32 v16, v53, v16
	v_exp_f32_e32 v57, v13
	v_fma_f32 v13, v15, s44, -v5
	v_add_f32_e32 v16, v54, v16
	v_exp_f32_e32 v58, v13
	v_fma_f32 v6, v6, s44, -v5
	v_add_f32_e32 v12, v55, v16
	v_exp_f32_e32 v59, v6
	v_fma_f32 v7, v7, s44, -v5
	v_add_f32_e32 v12, v56, v12
	v_exp_f32_e32 v60, v7
	v_fma_f32 v7, v8, s44, -v5
	v_add_f32_e32 v12, v57, v12
	v_exp_f32_e32 v61, v7
	v_fma_f32 v7, v9, s44, -v5
	v_add_f32_e32 v12, v58, v12
	v_exp_f32_e32 v62, v7
	v_add_f32_e32 v6, v59, v12
	v_add_f32_e32 v6, v60, v6
	v_add_f32_e32 v6, v61, v6
	v_add_f32_e32 v6, v62, v6
	ds_bpermute_b32 v7, v104, v6
	v_cvt_pk_f16_f32 v9, v38, v39
	v_cvt_pk_f16_f32 v8, v36, v37
	v_fma_f32 v4, v4, s11, -v5
	v_exp_f32_e32 v4, v4
	s_waitcnt lgkmcnt(0)
; #define LAS __attribute__((address_space(3)))
; __device__ __forceinline__ float shx(float v, int lane, int m) { return __builtin_bit_cast(float, __builtin_amdgcn_ds_bpermute((lane ^ m) << 2, __builtin_bit_cast(int, v))); }
; __device__ __forceinline__ float ex2(float x) { return __builtin_amdgcn_exp2f(x); }
; __device__ __forceinline__ h4 tr_read(const LAS half_t* p) { s4v r = __builtin_amdgcn_ds_read_tr16_b64_v4i16((LAS s4v*)p); return __builtin_bit_cast(h4, r); }
; template <bool FIRST>
; __device__ __forceinline__ void swa_item(const Params& p, int l, LAS unsigned char* lds, int item, int tid, int wave, int lane) {
;     ...
;         ls += shx(ls, lane, 16); ls += shx(ls, lane, 32);
;         ls += ex2(sink2 - m);
;         const float inv = __builtin_amdgcn_rcpf(ls);
;         f32x4 o[4];
; #pragma unroll
;         for (int i = 0; i < 4; ++i) o[i] = (f32x4){0.f, 0.f, 0.f, 0.f};
; #pragma unroll
;         for (int pr = 0; pr < 5; ++pr) {
;             h8 bp;
; #pragma unroll
;             for (int e = 0; e < 4; ++e) { bp[e] = (half_t)s[2 * pr][e]; bp[4 + e] = (pr < 4) ? (half_t)s[(pr < 4) ? 2 * pr + 1 : 0][e] : (half_t)0.f; }
; #pragma unroll
;             for (int mt = 0; mt < 4; ++mt) { const LAS half_t* vp = Vs + ((wave + 2 * pr) * 16 + 4 * g + q) * SSTR + mt * 16 + 4 * pp;
;                 const h8 af = cat8(tr_read(vp), tr_read(vp + 16 * SSTR));
;                 o[mt] = __builtin_amdgcn_mfma_f32_16x16x32_f16(af, bp, o[mt], 0, 0, 0); }
;         }
	v_add_f32_e32 v63, v6, v7
	v_cvt_pk_f16_f32 v6, v10, v11
	ds_read_b64_tr_b16 v[12:13], v115 offset:41472
	ds_read_b64_tr_b16 v[10:11], v115 offset:39168
	ds_read_b64_tr_b16 v[14:15], v115 offset:39200
	ds_read_b64_tr_b16 v[16:17], v115 offset:41504
	ds_read_b64_tr_b16 v[18:19], v115 offset:39232
	ds_read_b64_tr_b16 v[20:21], v115 offset:41536
	ds_read_b64_tr_b16 v[22:23], v115 offset:39264
	ds_read_b64_tr_b16 v[24:25], v115 offset:41568
	v_cvt_pk_f16_f32 v7, v40, v41
	ds_bpermute_b32 v64, v105, v63
	s_waitcnt lgkmcnt(0)
	v_add_f32_e32 v5, v63, v64
	v_mfma_f32_16x16x32_f16 v[10:13], v[10:13], v[6:9], 0
	v_mfma_f32_16x16x32_f16 v[14:17], v[14:17], v[6:9], 0
	v_mfma_f32_16x16x32_f16 v[18:21], v[18:21], v[6:9], 0
	v_mfma_f32_16x16x32_f16 v[6:9], v[22:25], v[6:9], 0
	v_cvt_pk_f16_f32 v24, v28, v29
	ds_read_b64_tr_b16 v[26:27], v115 offset:43776
	ds_read_b64_tr_b16 v[28:29], v115 offset:46080
	v_cvt_pk_f16_f32 v25, v30, v31
	v_cvt_pk_f16_f32 v23, v34, v35
	v_cvt_pk_f16_f32 v22, v32, v33
	v_add_f32_e32 v34, v4, v5
	v_cvt_pk_f16_f32 v5, v61, v62
	s_waitcnt lgkmcnt(0)
	v_mfma_f32_16x16x32_f16 v[10:13], v[26:29], v[22:25], v[10:13]
	ds_read_b64_tr_b16 v[26:27], v115 offset:43808
	ds_read_b64_tr_b16 v[28:29], v115 offset:46112
	v_cvt_pk_f16_f32 v4, v59, v60
	s_waitcnt lgkmcnt(0)
	v_mfma_f32_16x16x32_f16 v[14:17], v[26:29], v[22:25], v[14:17]
	ds_read_b64_tr_b16 v[26:27], v115 offset:43840
	ds_read_b64_tr_b16 v[28:29], v115 offset:46144
	s_waitcnt lgkmcnt(0)
	v_mfma_f32_16x16x32_f16 v[18:21], v[26:29], v[22:25], v[18:21]
	ds_read_b64_tr_b16 v[26:27], v115 offset:43872
	ds_read_b64_tr_b16 v[28:29], v115 offset:46176
	s_waitcnt lgkmcnt(0)
	v_mfma_f32_16x16x32_f16 v[6:9], v[26:29], v[22:25], v[6:9]
	ds_read_b64_tr_b16 v[26:27], v115 offset:48384
	ds_read_b64_tr_b16 v[28:29], v115 offset:50688
	v_cvt_pk_f16_f32 v25, v49, v50
	v_cvt_pk_f16_f32 v24, v46, v47
	v_cvt_pk_f16_f32 v23, v44, v45
	v_cvt_pk_f16_f32 v22, v43, v42
	s_waitcnt lgkmcnt(0)
	s_nop 0
	v_mfma_f32_16x16x32_f16 v[10:13], v[26:29], v[22:25], v[10:13]
	ds_read_b64_tr_b16 v[26:27], v115 offset:48416
	ds_read_b64_tr_b16 v[28:29], v115 offset:50720
	s_waitcnt lgkmcnt(0)
	v_mfma_f32_16x16x32_f16 v[14:17], v[26:29], v[22:25], v[14:17]
	ds_read_b64_tr_b16 v[26:27], v115 offset:48448
	ds_read_b64_tr_b16 v[28:29], v115 offset:50752
	s_waitcnt lgkmcnt(0)
	v_mfma_f32_16x16x32_f16 v[18:21], v[26:29], v[22:25], v[18:21]
	ds_read_b64_tr_b16 v[26:27], v115 offset:48480
	ds_read_b64_tr_b16 v[28:29], v115 offset:50784
	s_waitcnt lgkmcnt(0)
	v_mfma_f32_16x16x32_f16 v[6:9], v[26:29], v[22:25], v[6:9]
	ds_read_b64_tr_b16 v[26:27], v115 offset:52992
	ds_read_b64_tr_b16 v[28:29], v115 offset:55296
	v_cvt_pk_f16_f32 v25, v57, v58
	v_cvt_pk_f16_f32 v24, v55, v56
	v_cvt_pk_f16_f32 v23, v53, v54
	v_cvt_pk_f16_f32 v22, v51, v52
	s_waitcnt lgkmcnt(0)
	s_nop 0
	v_mfma_f32_16x16x32_f16 v[10:13], v[26:29], v[22:25], v[10:13]
	ds_read_b64_tr_b16 v[26:27], v115 offset:53024
	ds_read_b64_tr_b16 v[28:29], v115 offset:55328
	s_waitcnt lgkmcnt(0)
	v_mfma_f32_16x16x32_f16 v[26:29], v[26:29], v[22:25], v[14:17]
	s_nop 2
	ds_read_b64_tr_b16 v[14:15], v115 offset:53056
	ds_read_b64_tr_b16 v[16:17], v115 offset:55360
	s_waitcnt lgkmcnt(0)
	v_mfma_f32_16x16x32_f16 v[30:33], v[14:17], v[22:25], v[18:21]
	ds_read_b64_tr_b16 v[14:15], v115 offset:53088
	ds_read_b64_tr_b16 v[16:17], v115 offset:55392
	s_waitcnt lgkmcnt(0)
	v_mfma_f32_16x16x32_f16 v[20:23], v[14:17], v[22:25], v[6:9]
	ds_read_b64_tr_b16 v[14:15], v115 offset:57600
	ds_read_b64_tr_b16 v[16:17], v115 offset:59904
	s_nop 0
	v_mov_b32_e32 v6, v3
	v_mov_b32_e32 v7, v3
	s_waitcnt lgkmcnt(0)
	s_nop 0
	v_mfma_f32_16x16x32_f16 v[16:19], v[14:17], v[4:7], v[10:13]
	ds_read_b64_tr_b16 v[8:9], v115 offset:57632
	s_nop 1
	ds_read_b64_tr_b16 v[10:11], v115 offset:59936
	s_waitcnt lgkmcnt(0)
	v_mfma_f32_16x16x32_f16 v[12:15], v[8:11], v[4:7], v[26:29]
	ds_read_b64_tr_b16 v[8:9], v115 offset:57664
	ds_read_b64_tr_b16 v[10:11], v115 offset:59968
	ds_read_b64_tr_b16 v[24:25], v115 offset:57696
	ds_read_b64_tr_b16 v[26:27], v115 offset:60000
	s_waitcnt lgkmcnt(2)
	v_mfma_f32_16x16x32_f16 v[8:11], v[8:11], v[4:7], v[30:33]
	s_waitcnt lgkmcnt(0)
; __device__ __forceinline__ float siluf(float x) { return x * __builtin_amdgcn_rcpf(1.f + ex2(x * -1.44269504f)); }
; template <bool FIRST>
; __device__ __forceinline__ void swa_item(const Params& p, int l, LAS unsigned char* lds, int item, int tid, int wave, int lane) {
;     ...
; #pragma unroll
;         for (int mt = 0; mt < 4; ++mt) { const int col = hq * 64 + mt * 16 + 4 * g;
;             const h4 sg = *(const h4*)(PR + (size_t)tok * NIN + C_SG + col);
;             h4 y;
; #pragma unroll
;             for (int e = 0; e < 4; ++e) y[e] = op16(o[mt][e] * inv * siluf((float)sg[e]), TAIL_BF16);
;             *(h4*)(RA + (size_t)tok * 4096 + 2048 + col) = y; }
;     }
;     __syncthreads();
	v_mfma_f32_16x16x32_f16 v[4:7], v[24:27], v[4:7], v[20:23]
	s_nop 2
	v_or_b32_e32 v22, 0x180, v48
	v_mov_b32_e32 v23, v3
	v_lshl_add_u64 v[24:25], v[88:89], 0, v[22:23]
	v_mov_b32_e32 v24, v216
	v_rcp_f32_e32 v20, v34
	v_mov_b32_e32 v25, v217
	v_cvt_f32_f16_e32 v26, v24
	v_cvt_f32_f16_sdwa v27, v24 dst_sel:DWORD dst_unused:UNUSED_PAD src0_sel:WORD_1
	v_cvt_f32_f16_e32 v24, v25
	v_cvt_f32_f16_sdwa v25, v25 dst_sel:DWORD dst_unused:UNUSED_PAD src0_sel:WORD_1
	v_mul_f32_e32 v21, 0xbfb8aa3b, v26
	v_exp_f32_e32 v21, v21
	s_nop 0
	v_add_f32_e32 v21, 1.0, v21
	v_rcp_f32_e32 v28, v21
	v_pk_mul_f32 v[16:17], v[20:21], v[16:17] op_sel_hi:[0,1]
	v_mul_f32_e32 v21, 0xbfb8aa3b, v27
	v_exp_f32_e32 v21, v21
	s_nop 0
	v_add_f32_e32 v21, 1.0, v21
	v_rcp_f32_e32 v29, v21
	v_pk_mul_f32 v[18:19], v[20:21], v[18:19] op_sel_hi:[0,1]
	v_pk_mul_f32 v[12:13], v[20:21], v[12:13] op_sel_hi:[0,1]
	v_pk_mul_f32 v[14:15], v[20:21], v[14:15] op_sel_hi:[0,1]
	v_pk_mul_f32 v[26:27], v[28:29], v[26:27]
	v_pk_mul_f32 v[8:9], v[20:21], v[8:9] op_sel_hi:[0,1]
	v_pk_mul_f32 v[16:17], v[16:17], v[26:27]
	v_pk_mul_f32 v[10:11], v[20:21], v[10:11] op_sel_hi:[0,1]
	v_cvt_pk_bf16_f32 v16, v16, v17
	v_mul_f32_e32 v17, 0xbfb8aa3b, v24
	v_exp_f32_e32 v17, v17
	v_pk_mul_f32 v[4:5], v[20:21], v[4:5] op_sel_hi:[0,1]
	v_pk_mul_f32 v[6:7], v[20:21], v[6:7] op_sel_hi:[0,1]
	v_add_f32_e32 v17, 1.0, v17
	v_rcp_f32_e32 v26, v17
	v_mul_f32_e32 v17, 0xbfb8aa3b, v25
	v_exp_f32_e32 v17, v17
	s_nop 0
	v_add_f32_e32 v17, 1.0, v17
	v_rcp_f32_e32 v27, v17
	s_nop 0
	v_pk_mul_f32 v[24:25], v[26:27], v[24:25]
	s_nop 0
	v_pk_mul_f32 v[18:19], v[18:19], v[24:25]
	s_nop 0
	v_cvt_pk_bf16_f32 v17, v18, v19
	v_lshl_add_u64 v[18:19], v[0:1], 0, v[22:23]
	global_store_dwordx2 v[18:19], v[16:17], off
	v_or_b32_e32 v16, 0x1a0, v48
	v_mov_b32_e32 v17, v3
	v_lshl_add_u64 v[18:19], v[88:89], 0, v[16:17]
	v_mov_b32_e32 v18, v218
	v_mov_b32_e32 v19, v219
	v_cvt_f32_f16_e32 v22, v18
	v_cvt_f32_f16_sdwa v23, v18 dst_sel:DWORD dst_unused:UNUSED_PAD src0_sel:WORD_1
	v_mul_f32_e32 v18, 0xbfb8aa3b, v22
	v_exp_f32_e32 v18, v18
	s_nop 0
	v_add_f32_e32 v18, 1.0, v18
	v_rcp_f32_e32 v24, v18
	v_mul_f32_e32 v18, 0xbfb8aa3b, v23
	v_exp_f32_e32 v18, v18
	s_nop 0
	v_add_f32_e32 v18, 1.0, v18
	v_rcp_f32_e32 v25, v18
	v_cvt_f32_f16_e32 v18, v19
	v_cvt_f32_f16_sdwa v19, v19 dst_sel:DWORD dst_unused:UNUSED_PAD src0_sel:WORD_1
	v_pk_mul_f32 v[22:23], v[24:25], v[22:23]
	s_nop 0
	v_pk_mul_f32 v[12:13], v[12:13], v[22:23]
	s_nop 0
	v_cvt_pk_bf16_f32 v12, v12, v13
	v_mul_f32_e32 v13, 0xbfb8aa3b, v18
	v_exp_f32_e32 v13, v13
	s_nop 0
	v_add_f32_e32 v13, 1.0, v13
	v_rcp_f32_e32 v22, v13
	v_mul_f32_e32 v13, 0xbfb8aa3b, v19
	v_exp_f32_e32 v13, v13
	s_nop 0
	v_add_f32_e32 v13, 1.0, v13
	v_rcp_f32_e32 v23, v13
	s_nop 0
	v_pk_mul_f32 v[18:19], v[22:23], v[18:19]
	s_nop 0
	v_pk_mul_f32 v[14:15], v[14:15], v[18:19]
	s_nop 0
	v_cvt_pk_bf16_f32 v13, v14, v15
	v_lshl_add_u64 v[14:15], v[0:1], 0, v[16:17]
	global_store_dwordx2 v[14:15], v[12:13], off
	v_or_b32_e32 v12, 0x1c0, v48
	v_mov_b32_e32 v13, v3
	v_lshl_add_u64 v[14:15], v[88:89], 0, v[12:13]
	v_mov_b32_e32 v14, v220
	v_mov_b32_e32 v15, v221
	v_cvt_f32_f16_e32 v16, v14
	v_cvt_f32_f16_sdwa v17, v14 dst_sel:DWORD dst_unused:UNUSED_PAD src0_sel:WORD_1
	v_mul_f32_e32 v14, 0xbfb8aa3b, v16
	v_exp_f32_e32 v14, v14
	s_nop 0
	v_add_f32_e32 v14, 1.0, v14
	v_rcp_f32_e32 v18, v14
	v_mul_f32_e32 v14, 0xbfb8aa3b, v17
	v_exp_f32_e32 v14, v14
	s_nop 0
	v_add_f32_e32 v14, 1.0, v14
	v_rcp_f32_e32 v19, v14
	v_cvt_f32_f16_e32 v14, v15
	v_cvt_f32_f16_sdwa v15, v15 dst_sel:DWORD dst_unused:UNUSED_PAD src0_sel:WORD_1
	v_pk_mul_f32 v[16:17], v[18:19], v[16:17]
	s_nop 0
	v_pk_mul_f32 v[8:9], v[8:9], v[16:17]
	s_nop 0
	v_cvt_pk_bf16_f32 v8, v8, v9
	v_mul_f32_e32 v9, 0xbfb8aa3b, v14
	v_exp_f32_e32 v9, v9
	s_nop 0
	v_add_f32_e32 v9, 1.0, v9
	v_rcp_f32_e32 v16, v9
	v_mul_f32_e32 v9, 0xbfb8aa3b, v15
	v_exp_f32_e32 v9, v9
	s_nop 0
	v_add_f32_e32 v9, 1.0, v9
	v_rcp_f32_e32 v17, v9
	s_nop 0
	v_pk_mul_f32 v[14:15], v[16:17], v[14:15]
	s_nop 0
	v_pk_mul_f32 v[10:11], v[10:11], v[14:15]
	s_nop 0
	v_cvt_pk_bf16_f32 v9, v10, v11
	v_lshl_add_u64 v[10:11], v[0:1], 0, v[12:13]
	global_store_dwordx2 v[10:11], v[8:9], off
	v_or_b32_e32 v8, 0x1e0, v48
	v_mov_b32_e32 v9, v3
	v_lshl_add_u64 v[10:11], v[88:89], 0, v[8:9]
	v_mov_b32_e32 v10, v222
	v_lshl_add_u64 v[0:1], v[0:1], 0, v[8:9]
	v_mov_b32_e32 v11, v223
	v_cvt_f32_f16_e32 v12, v10
	v_cvt_f32_f16_sdwa v13, v10 dst_sel:DWORD dst_unused:UNUSED_PAD src0_sel:WORD_1
	v_mul_f32_e32 v10, 0xbfb8aa3b, v12
	v_exp_f32_e32 v10, v10
	s_nop 0
	v_add_f32_e32 v10, 1.0, v10
	v_rcp_f32_e32 v14, v10
	v_mul_f32_e32 v10, 0xbfb8aa3b, v13
	v_exp_f32_e32 v10, v10
	s_nop 0
	v_add_f32_e32 v10, 1.0, v10
	v_rcp_f32_e32 v15, v10
	v_cvt_f32_f16_e32 v10, v11
	v_cvt_f32_f16_sdwa v11, v11 dst_sel:DWORD dst_unused:UNUSED_PAD src0_sel:WORD_1
	v_pk_mul_f32 v[12:13], v[14:15], v[12:13]
	s_nop 0
	v_pk_mul_f32 v[4:5], v[4:5], v[12:13]
	s_nop 0
	v_cvt_pk_bf16_f32 v4, v4, v5
	v_mul_f32_e32 v5, 0xbfb8aa3b, v10
	v_exp_f32_e32 v5, v5
	s_nop 0
	v_add_f32_e32 v5, 1.0, v5
	v_rcp_f32_e32 v12, v5
	v_mul_f32_e32 v5, 0xbfb8aa3b, v11
	v_exp_f32_e32 v5, v5
	s_nop 0
	v_add_f32_e32 v5, 1.0, v5
	v_rcp_f32_e32 v13, v5
	s_nop 0
	v_pk_mul_f32 v[10:11], v[12:13], v[10:11]
	s_nop 0
	v_pk_mul_f32 v[6:7], v[6:7], v[10:11]
	s_nop 0
	v_cvt_pk_bf16_f32 v5, v6, v7
	global_store_dwordx2 v[0:1], v[4:5], off
	s_barrier
	s_branch .LBB0_388
